# peel first K-loop iteration in all 5 GEMM phases with SrcC=0 MFMAs, accumulator zeroing (128 v_mov per unit) deleted; on top of hand-written EpiGate + trim15
# speedup vs baseline: 1.0091x; 1.0030x over previous
;     __host__ __device__ bool next(int i, Unit& u) const { return at((long)i * G + c, u); }
; #define PG8_STAGE(bufoff, gbase, voff) do { _Pragma("unroll") for (int _i = 0; _i < 2; ++_i) \
;         __builtin_amdgcn_global_load_lds((const unsigned*)((const char*)(gbase) + (voff)[_i]), (PG8_LAS unsigned*)(lds + (bufoff) + ldsw + _i * 8192), 16, 0, 0); } while (0)
; #define PG8_LDA(dst, b, h) do { _Pragma("unroll") for (int m = 0; m < 4; ++m) _Pragma("unroll") for (int k = 0; k < 2; ++k) dst[m][k] = *(const PG8_LAS bf16x8*)(lds + PG8_SA(b, h) + aoff + m * 2048 + k * 1024); } while (0)
; #define PG8_LDB(dst, b, h) do { _Pragma("unroll") for (int n = 0; n < 2; ++n) _Pragma("unroll") for (int k = 0; k < 2; ++k) dst[n][k] = *(const PG8_LAS bf16x8*)(lds + PG8_SB(b, h) + boff + n * 2048 + k * 1024); } while (0)
; #define PG8_WAIT_V(n) asm volatile("s_waitcnt vmcnt(" #n ")" ::: "memory")
; #define PG8_BAR __builtin_amdgcn_s_barrier()
; template <class Epi, class Sched, bool ALIGN_EPI = false, bool SP2 = false>
; __device__ __forceinline__ void gemm_phase(PG8_LAS unsigned char* lds, const Gemm g, const Sched& S, const Epi& E) {
;     ...
;         const bool has_next = S.next(ui + 1, nxt);
;         const char* nA = has_next ? (const char*)g.A + (size_t)nxt.pm * tstep + (size_t)nxt.k0 * kstep : cA; const char* nB = has_next ? (const char*)g.Bt + (size_t)nxt.pn * tstep + (size_t)nxt.k0 * kstep : cB;
;         const int nt = cur.nt;
;         for (int t = 0; t < nt; t += 2) {
;             const bool last = (t == nt - 2);
;             const char* a1 = cA + (size_t)(t + 1) * kstep;
;             const char* a2 = last ? nA : cA + (size_t)(t + 2) * kstep; const char* b2 = last ? nB : cB + (size_t)(t + 2) * kstep;
;             const char* a3 = a2 + kstep; const char* b3 = b2 + kstep;
;             if (last && has_next) S.a_ready(nxt);
;             if constexpr (SP2) {
;             PG8_LDB(B0, 0, 0); PG8_LDB(B1, 0, 1); PG8_SCHED; PG8_LDA(At, 0, 0); PG8_STAGE(PG8_SA(1, 1), a1 + hstep, voffA);
;             PG8_WAIT_V(8); PG8_WAIT_L(0); PG8_BAR; PG8_MMA(0, 0, At, B0); PG8_MMA(0, 1, At, B1); PG8_BAR; PG8_SCHED;
;             PG8_LDA(At, 0, 1); PG8_STAGE(PG8_SB(0, 0), b2, voffB); PG8_STAGE(PG8_SB(0, 1), b2 + hstep, voffB); PG8_STAGE(PG8_SA(0, 0), a2, voffA);
;             PG8_WAIT_V(8); PG8_WAIT_L(0); PG8_BAR; PG8_MMA(1, 0, At, B0); PG8_MMA(1, 1, At, B1); PG8_BAR; PG8_SCHED;
.LBB0_123:
	s_ashr_i32 s55, s54, 31
	s_lshl_b64 s[16:17], s[54:55], 21
	s_add_u32 s58, s4, s16
	s_addc_u32 s59, s5, s17
	s_and_b64 s[16:17], s[56:57], exec
	s_cselect_b32 s30, s59, s29
	s_cselect_b32 s31, s58, s28
	s_ashr_i32 s53, s52, 31
	s_lshl_b64 s[16:17], s[52:53], 21
	s_add_u32 s60, s6, s16
	s_addc_u32 s61, s7, s17
	s_and_b64 s[16:17], s[56:57], exec
	s_cselect_b32 s53, s61, s27
	s_cselect_b32 s55, s60, s26
	s_add_u32 vcc_lo, s26, 0x100
	s_addc_u32 s16, s27, 0
	s_add_u32 s62, s28, 0x100080
	s_addc_u32 s63, s29, 0
	s_mov_b32 s17, -2
	s_waitcnt vmcnt(0)
	s_add_u32 s26, s62, 0xfff00080
	s_addc_u32 s27, s63, -1
	s_add_i32 s65, 0, 0x10000
	s_cmp_eq_u32 s17, 60
	s_cselect_b32 s29, s30, s27
	s_cselect_b32 s28, s31, s26
	v_add_u32_e32 v170, s65, v182
	s_cselect_b32 s27, s53, s16
	s_cselect_b32 s26, s55, vcc_lo
	s_add_i32 s70, 0, 0x14000
	ds_read_b128 v[122:125], v170
	ds_read_b128 v[126:129], v170 offset:1024
	ds_read_b128 v[130:133], v170 offset:2048
	ds_read_b128 v[172:175], v170 offset:3072
	v_add_u32_e32 v170, s70, v182
	ds_read_b128 v[176:179], v170
	ds_read_b128 v[192:195], v170 offset:1024
	ds_read_b128 v[196:199], v170 offset:2048
	ds_read_b128 v[200:203], v170 offset:3072
	v_lshl_add_u64 v[180:181], s[62:63], 0, v[156:157]
	s_add_i32 m0, s10, 0xc000
	ds_read_b128 v[204:207], v191
	ds_read_b128 v[220:223], v191 offset:1024
	ds_read_b128 v[224:227], v191 offset:2048
	ds_read_b128 v[228:231], v191 offset:3072
	ds_read_b128 v[232:235], v191 offset:4096
	ds_read_b128 v[236:239], v191 offset:5120
	ds_read_b128 v[240:243], v191 offset:6144
	ds_read_b128 v[244:247], v191 offset:7168
	global_load_lds_dwordx4 v[180:181], off
	v_lshl_add_u64 v[180:181], s[62:63], 0, v[154:155]
	s_add_i32 m0, s10, 0xe000
	s_nop 0
	global_load_lds_dwordx4 v[180:181], off
	s_waitcnt vmcnt(8)
	s_waitcnt lgkmcnt(0)
	s_setprio 1
	s_barrier
	v_mfma_f32_16x16x32_bf16 v[118:121], v[122:125], v[204:207], 0
	v_mfma_f32_16x16x32_bf16 v[138:141], v[130:133], v[204:207], 0
	v_mfma_f32_16x16x32_bf16 v[102:105], v[122:125], v[224:227], 0
	v_mfma_f32_16x16x32_bf16 v[114:117], v[130:133], v[224:227], 0
	v_mfma_f32_16x16x32_bf16 v[86:89], v[122:125], v[232:235], 0
	v_mfma_f32_16x16x32_bf16 v[98:101], v[130:133], v[232:235], 0
	v_mfma_f32_16x16x32_bf16 v[70:73], v[122:125], v[240:243], 0
	v_mfma_f32_16x16x32_bf16 v[82:85], v[130:133], v[240:243], 0
	v_mfma_f32_16x16x32_bf16 v[118:121], v[126:129], v[220:223], v[118:121]
	v_mfma_f32_16x16x32_bf16 v[138:141], v[172:175], v[220:223], v[138:141]
	v_mfma_f32_16x16x32_bf16 v[102:105], v[126:129], v[228:231], v[102:105]
	v_mfma_f32_16x16x32_bf16 v[114:117], v[172:175], v[228:231], v[114:117]
	v_mfma_f32_16x16x32_bf16 v[86:89], v[126:129], v[236:239], v[86:89]
	v_mfma_f32_16x16x32_bf16 v[98:101], v[172:175], v[236:239], v[98:101]
	v_mfma_f32_16x16x32_bf16 v[70:73], v[126:129], v[244:247], v[70:73]
	v_mfma_f32_16x16x32_bf16 v[82:85], v[172:175], v[244:247], v[82:85]
	v_mfma_f32_16x16x32_bf16 v[134:137], v[176:179], v[204:207], 0
	v_mfma_f32_16x16x32_bf16 v[110:113], v[196:199], v[204:207], 0
	v_mfma_f32_16x16x32_bf16 v[106:109], v[176:179], v[224:227], 0
	v_mfma_f32_16x16x32_bf16 v[94:97], v[196:199], v[224:227], 0
	v_mfma_f32_16x16x32_bf16 v[90:93], v[176:179], v[232:235], 0
	v_mfma_f32_16x16x32_bf16 v[78:81], v[196:199], v[232:235], 0
	v_mfma_f32_16x16x32_bf16 v[74:77], v[176:179], v[240:243], 0
	v_mfma_f32_16x16x32_bf16 v[66:69], v[196:199], v[240:243], 0
	v_mfma_f32_16x16x32_bf16 v[134:137], v[192:195], v[220:223], v[134:137]
	v_mfma_f32_16x16x32_bf16 v[110:113], v[200:203], v[220:223], v[110:113]
	v_mfma_f32_16x16x32_bf16 v[106:109], v[192:195], v[228:231], v[106:109]
	v_mfma_f32_16x16x32_bf16 v[94:97], v[200:203], v[228:231], v[94:97]
	v_mfma_f32_16x16x32_bf16 v[90:93], v[192:195], v[236:239], v[90:93]
	v_mfma_f32_16x16x32_bf16 v[78:81], v[200:203], v[236:239], v[78:81]
	v_mfma_f32_16x16x32_bf16 v[74:77], v[192:195], v[244:247], v[74:77]
	v_mfma_f32_16x16x32_bf16 v[66:69], v[200:203], v[244:247], v[66:69]
	s_barrier
	s_setprio 0
	s_add_i32 s65, s65, s9
	v_lshl_add_u64 v[180:181], s[26:27], 0, v[158:159]
	s_mov_b32 m0, s65
	ds_read_b128 v[204:207], v191 offset:16384
	ds_read_b128 v[220:223], v191 offset:17408
	ds_read_b128 v[224:227], v191 offset:18432
	ds_read_b128 v[228:231], v191 offset:19456
	ds_read_b128 v[232:235], v191 offset:20480
	ds_read_b128 v[236:239], v191 offset:21504
	ds_read_b128 v[240:243], v191 offset:22528
	ds_read_b128 v[244:247], v191 offset:23552
	global_load_lds_dwordx4 v[180:181], off
	s_add_i32 m0, s65, 0x2000
	s_add_u32 s68, s26, 0x100000
	v_lshl_add_u64 v[208:209], s[26:27], 0, v[142:143]
	s_addc_u32 s69, s27, 0
	s_add_i32 s65, s70, s9
	global_load_lds_dwordx4 v[208:209], off
	v_lshl_add_u64 v[248:249], s[68:69], 0, v[158:159]
	s_mov_b32 m0, s65
	v_lshl_add_u64 v[170:171], s[28:29], 0, v[144:145]
	global_load_lds_dwordx4 v[248:249], off
	v_lshl_add_u64 v[248:249], s[68:69], 0, v[142:143]
	s_add_i32 m0, s65, 0x2000
	s_nop 0
	global_load_lds_dwordx4 v[248:249], off
	v_lshl_add_u64 v[248:249], s[28:29], 0, v[146:147]
	s_mov_b32 m0, s10
	s_nop 0
	global_load_lds_dwordx4 v[248:249], off
	s_mov_b32 m0, s11
	s_nop 0
	global_load_lds_dwordx4 v[170:171], off
	s_waitcnt vmcnt(8)
	s_waitcnt lgkmcnt(0)
	s_setprio 1
	s_barrier
; #define PG8_STAGE(bufoff, gbase, voff) do { _Pragma("unroll") for (int _i = 0; _i < 2; ++_i) \
;         __builtin_amdgcn_global_load_lds((const unsigned*)((const char*)(gbase) + (voff)[_i]), (PG8_LAS unsigned*)(lds + (bufoff) + ldsw + _i * 8192), 16, 0, 0); } while (0)
; #define PG8_LDA(dst, b, h) do { _Pragma("unroll") for (int m = 0; m < 4; ++m) _Pragma("unroll") for (int k = 0; k < 2; ++k) dst[m][k] = *(const PG8_LAS bf16x8*)(lds + PG8_SA(b, h) + aoff + m * 2048 + k * 1024); } while (0)
; #define PG8_LDB(dst, b, h) do { _Pragma("unroll") for (int n = 0; n < 2; ++n) _Pragma("unroll") for (int k = 0; k < 2; ++k) dst[n][k] = *(const PG8_LAS bf16x8*)(lds + PG8_SB(b, h) + boff + n * 2048 + k * 1024); } while (0)
; #define PG8_MMA(ai, bj, At, Bt) do { __builtin_amdgcn_s_setprio(1); _Pragma("unroll") for (int m = 0; m < 4; ++m) _Pragma("unroll") for (int n = 0; n < 2; ++n) _Pragma("unroll") for (int k = 0; k < 2; ++k) \
;         acc[ai][bj][m][n] = __builtin_amdgcn_mfma_f32_16x16x32_bf16(Bt[n][k], At[m][k], acc[ai][bj][m][n], 0, 0, 0); __builtin_amdgcn_s_setprio(0); } while (0)
; #define PG8_WAIT_V(n) asm volatile("s_waitcnt vmcnt(" #n ")" ::: "memory")
; #define PG8_WAIT_L(n) asm volatile("s_waitcnt lgkmcnt(" #n ")" ::: "memory")
; #define PG8_BAR __builtin_amdgcn_s_barrier()
; #define PG8_SCHED __builtin_amdgcn_sched_barrier(0)
; template <class Epi, class Sched, bool ALIGN_EPI = false, bool SP2 = false>
; __device__ __forceinline__ void gemm_phase(PG8_LAS unsigned char* lds, const Gemm g, const Sched& S, const Epi& E) {
;     ...
;             PG8_WAIT_V(8); PG8_WAIT_L(0); PG8_BAR; PG8_MMA(1, 0, At, B0); PG8_MMA(1, 1, At, B1); PG8_BAR; PG8_SCHED;
;             PG8_LDB(B0, 1, 0); PG8_LDB(B1, 1, 1); PG8_SCHED; PG8_LDA(At, 1, 0); PG8_STAGE(PG8_SA(0, 1), a2 + hstep, voffA);
;             PG8_WAIT_V(8); PG8_WAIT_L(0); PG8_BAR; PG8_MMA(0, 0, At, B0); PG8_MMA(0, 1, At, B1); PG8_BAR; PG8_SCHED;
	v_mfma_f32_16x16x32_bf16 v[54:57], v[122:125], v[204:207], 0
	v_mfma_f32_16x16x32_bf16 v[62:65], v[130:133], v[204:207], 0
	v_mfma_f32_16x16x32_bf16 v[38:41], v[122:125], v[224:227], 0
	v_mfma_f32_16x16x32_bf16 v[50:53], v[130:133], v[224:227], 0
	v_mfma_f32_16x16x32_bf16 v[22:25], v[122:125], v[232:235], 0
	v_mfma_f32_16x16x32_bf16 v[34:37], v[130:133], v[232:235], 0
	v_mfma_f32_16x16x32_bf16 v[6:9], v[122:125], v[240:243], 0
	v_mfma_f32_16x16x32_bf16 v[18:21], v[130:133], v[240:243], 0
	v_mfma_f32_16x16x32_bf16 v[54:57], v[126:129], v[220:223], v[54:57]
	v_mfma_f32_16x16x32_bf16 v[62:65], v[172:175], v[220:223], v[62:65]
	v_mfma_f32_16x16x32_bf16 v[38:41], v[126:129], v[228:231], v[38:41]
	v_mfma_f32_16x16x32_bf16 v[50:53], v[172:175], v[228:231], v[50:53]
	v_mfma_f32_16x16x32_bf16 v[22:25], v[126:129], v[236:239], v[22:25]
	v_mfma_f32_16x16x32_bf16 v[34:37], v[172:175], v[236:239], v[34:37]
	v_mfma_f32_16x16x32_bf16 v[6:9], v[126:129], v[244:247], v[6:9]
	v_mfma_f32_16x16x32_bf16 v[18:21], v[172:175], v[244:247], v[18:21]
	v_mfma_f32_16x16x32_bf16 v[58:61], v[176:179], v[204:207], 0
	v_mfma_f32_16x16x32_bf16 v[46:49], v[196:199], v[204:207], 0
	v_mfma_f32_16x16x32_bf16 v[42:45], v[176:179], v[224:227], 0
	v_mfma_f32_16x16x32_bf16 v[30:33], v[196:199], v[224:227], 0
	v_mfma_f32_16x16x32_bf16 v[26:29], v[176:179], v[232:235], 0
	v_mfma_f32_16x16x32_bf16 v[14:17], v[196:199], v[232:235], 0
	v_mfma_f32_16x16x32_bf16 v[10:13], v[176:179], v[240:243], 0
	v_mfma_f32_16x16x32_bf16 v[2:5], v[196:199], v[240:243], 0
	v_mfma_f32_16x16x32_bf16 v[58:61], v[192:195], v[220:223], v[58:61]
	v_mfma_f32_16x16x32_bf16 v[46:49], v[200:203], v[220:223], v[46:49]
	v_mfma_f32_16x16x32_bf16 v[42:45], v[192:195], v[228:231], v[42:45]
	v_mfma_f32_16x16x32_bf16 v[30:33], v[200:203], v[228:231], v[30:33]
	v_mfma_f32_16x16x32_bf16 v[26:29], v[192:195], v[236:239], v[26:29]
	v_mfma_f32_16x16x32_bf16 v[14:17], v[200:203], v[236:239], v[14:17]
	v_mfma_f32_16x16x32_bf16 v[10:13], v[192:195], v[244:247], v[10:13]
	v_mfma_f32_16x16x32_bf16 v[2:5], v[200:203], v[244:247], v[2:5]
	s_barrier
	s_setprio 0
	s_add_i32 s65, 0, 0x18000
	s_add_i32 s68, 0, 0x1c000
	v_add_u32_e32 v172, s65, v182
	v_add_u32_e32 v200, s68, v182
	ds_read_b128 v[122:125], v172
	ds_read_b128 v[126:129], v172 offset:1024
	ds_read_b128 v[130:133], v172 offset:2048
	ds_read_b128 v[172:175], v172 offset:3072
	ds_read_b128 v[176:179], v200
	ds_read_b128 v[192:195], v200 offset:1024
	ds_read_b128 v[196:199], v200 offset:2048
	ds_read_b128 v[200:203], v200 offset:3072
	s_add_u32 s28, s28, 0x100000
	s_addc_u32 s29, s29, 0
	s_mov_b32 m0, s12
	v_lshl_add_u64 v[210:211], s[28:29], 0, v[146:147]
	ds_read_b128 v[204:207], v191 offset:32768
	ds_read_b128 v[220:223], v191 offset:33792
	ds_read_b128 v[224:227], v191 offset:34816
	ds_read_b128 v[228:231], v191 offset:35840
	ds_read_b128 v[232:235], v191 offset:36864
	ds_read_b128 v[236:239], v191 offset:37888
	ds_read_b128 v[240:243], v191 offset:38912
	ds_read_b128 v[244:247], v191 offset:39936
	global_load_lds_dwordx4 v[210:211], off
	v_lshl_add_u64 v[210:211], s[28:29], 0, v[144:145]
	s_mov_b32 m0, s13
	s_nop 0
	global_load_lds_dwordx4 v[210:211], off
	s_waitcnt vmcnt(8)
	s_waitcnt lgkmcnt(0)
	s_setprio 1
	s_barrier
	v_mfma_f32_16x16x32_bf16 v[118:121], v[122:125], v[204:207], v[118:121]
	v_mfma_f32_16x16x32_bf16 v[138:141], v[130:133], v[204:207], v[138:141]
	v_mfma_f32_16x16x32_bf16 v[102:105], v[122:125], v[224:227], v[102:105]
	v_mfma_f32_16x16x32_bf16 v[114:117], v[130:133], v[224:227], v[114:117]
	v_mfma_f32_16x16x32_bf16 v[86:89], v[122:125], v[232:235], v[86:89]
	v_mfma_f32_16x16x32_bf16 v[98:101], v[130:133], v[232:235], v[98:101]
	v_mfma_f32_16x16x32_bf16 v[70:73], v[122:125], v[240:243], v[70:73]
	v_mfma_f32_16x16x32_bf16 v[82:85], v[130:133], v[240:243], v[82:85]
	v_mfma_f32_16x16x32_bf16 v[118:121], v[126:129], v[220:223], v[118:121]
	v_mfma_f32_16x16x32_bf16 v[138:141], v[172:175], v[220:223], v[138:141]
	v_mfma_f32_16x16x32_bf16 v[102:105], v[126:129], v[228:231], v[102:105]
	v_mfma_f32_16x16x32_bf16 v[114:117], v[172:175], v[228:231], v[114:117]
	v_mfma_f32_16x16x32_bf16 v[86:89], v[126:129], v[236:239], v[86:89]
	v_mfma_f32_16x16x32_bf16 v[98:101], v[172:175], v[236:239], v[98:101]
	v_mfma_f32_16x16x32_bf16 v[70:73], v[126:129], v[244:247], v[70:73]
	v_mfma_f32_16x16x32_bf16 v[82:85], v[172:175], v[244:247], v[82:85]
	v_mfma_f32_16x16x32_bf16 v[134:137], v[176:179], v[204:207], v[134:137]
	v_mfma_f32_16x16x32_bf16 v[110:113], v[196:199], v[204:207], v[110:113]
	v_mfma_f32_16x16x32_bf16 v[106:109], v[176:179], v[224:227], v[106:109]
	v_mfma_f32_16x16x32_bf16 v[94:97], v[196:199], v[224:227], v[94:97]
	v_mfma_f32_16x16x32_bf16 v[90:93], v[176:179], v[232:235], v[90:93]
	v_mfma_f32_16x16x32_bf16 v[78:81], v[196:199], v[232:235], v[78:81]
	v_mfma_f32_16x16x32_bf16 v[74:77], v[176:179], v[240:243], v[74:77]
	v_mfma_f32_16x16x32_bf16 v[66:69], v[196:199], v[240:243], v[66:69]
	v_mfma_f32_16x16x32_bf16 v[134:137], v[192:195], v[220:223], v[134:137]
	v_mfma_f32_16x16x32_bf16 v[110:113], v[200:203], v[220:223], v[110:113]
	v_mfma_f32_16x16x32_bf16 v[106:109], v[192:195], v[228:231], v[106:109]
	v_mfma_f32_16x16x32_bf16 v[94:97], v[200:203], v[228:231], v[94:97]
	v_mfma_f32_16x16x32_bf16 v[90:93], v[192:195], v[236:239], v[90:93]
	v_mfma_f32_16x16x32_bf16 v[78:81], v[200:203], v[236:239], v[78:81]
	v_mfma_f32_16x16x32_bf16 v[74:77], v[192:195], v[244:247], v[74:77]
	v_mfma_f32_16x16x32_bf16 v[66:69], v[200:203], v[244:247], v[66:69]
	s_barrier
; #define PG8_STAGE(bufoff, gbase, voff) do { _Pragma("unroll") for (int _i = 0; _i < 2; ++_i) \
;         __builtin_amdgcn_global_load_lds((const unsigned*)((const char*)(gbase) + (voff)[_i]), (PG8_LAS unsigned*)(lds + (bufoff) + ldsw + _i * 8192), 16, 0, 0); } while (0)
; #define PG8_LDA(dst, b, h) do { _Pragma("unroll") for (int m = 0; m < 4; ++m) _Pragma("unroll") for (int k = 0; k < 2; ++k) dst[m][k] = *(const PG8_LAS bf16x8*)(lds + PG8_SA(b, h) + aoff + m * 2048 + k * 1024); } while (0)
; #define PG8_LDB(dst, b, h) do { _Pragma("unroll") for (int n = 0; n < 2; ++n) _Pragma("unroll") for (int k = 0; k < 2; ++k) dst[n][k] = *(const PG8_LAS bf16x8*)(lds + PG8_SB(b, h) + boff + n * 2048 + k * 1024); } while (0)
; template <class Epi, class Sched, bool ALIGN_EPI = false, bool SP2 = false>
; __device__ __forceinline__ void gemm_phase(PG8_LAS unsigned char* lds, const Gemm g, const Sched& S, const Epi& E) {
;     ...
;         for (int t = 0; t < nt; t += 2) {
;             const bool last = (t == nt - 2);
;             const char* a1 = cA + (size_t)(t + 1) * kstep;
;             const char* a2 = last ? nA : cA + (size_t)(t + 2) * kstep; const char* b2 = last ? nB : cB + (size_t)(t + 2) * kstep;
;             const char* a3 = a2 + kstep; const char* b3 = b2 + kstep;
;             if (last && has_next) S.a_ready(nxt);
;             if constexpr (SP2) {
;             PG8_LDB(B0, 0, 0); PG8_LDB(B1, 0, 1); PG8_SCHED; PG8_LDA(At, 0, 0); PG8_STAGE(PG8_SA(1, 1), a1 + hstep, voffA);
;             PG8_WAIT_V(8); PG8_WAIT_L(0); PG8_BAR; PG8_MMA(0, 0, At, B0); PG8_MMA(0, 1, At, B1); PG8_BAR; PG8_SCHED;
;             PG8_LDA(At, 0, 1); PG8_STAGE(PG8_SB(0, 0), b2, voffB); PG8_STAGE(PG8_SB(0, 1), b2 + hstep, voffB); PG8_STAGE(PG8_SA(0, 0), a2, voffA);
;             PG8_WAIT_V(8); PG8_WAIT_L(0); PG8_BAR; PG8_MMA(1, 0, At, B0); PG8_MMA(1, 1, At, B1); PG8_BAR; PG8_SCHED;
;             PG8_LDB(B0, 1, 0); PG8_LDB(B1, 1, 1); PG8_SCHED; PG8_LDA(At, 1, 0); PG8_STAGE(PG8_SA(0, 1), a2 + hstep, voffA);
;             PG8_WAIT_V(8); PG8_WAIT_L(0); PG8_BAR; PG8_MMA(0, 0, At, B0); PG8_MMA(0, 1, At, B1); PG8_BAR; PG8_SCHED;
;             PG8_LDA(At, 1, 1); PG8_STAGE(PG8_SB(1, 0), b3, voffB); PG8_STAGE(PG8_SB(1, 1), b3 + hstep, voffB); PG8_STAGE(PG8_SA(1, 0), a3, voffA);
;             PG8_WAIT_V(8); PG8_WAIT_L(0); PG8_BAR; PG8_MMA(1, 0, At, B0); PG8_MMA(1, 1, At, B1); PG8_BAR; PG8_SCHED;
	s_setprio 0
	s_add_i32 s28, s65, s9
	v_lshl_add_u64 v[180:181], v[180:181], 0, s[96:97]
	s_mov_b32 m0, s28
	ds_read_b128 v[204:207], v191 offset:49152
	ds_read_b128 v[220:223], v191 offset:50176
	ds_read_b128 v[224:227], v191 offset:51200
	ds_read_b128 v[228:231], v191 offset:52224
	ds_read_b128 v[232:235], v191 offset:53248
	ds_read_b128 v[236:239], v191 offset:54272
	ds_read_b128 v[240:243], v191 offset:55296
	ds_read_b128 v[244:247], v191 offset:56320
	global_load_lds_dwordx4 v[180:181], off
	s_add_i32 m0, s28, 0x2000
	s_add_u32 s26, s26, 0x100080
	v_lshl_add_u64 v[180:181], v[208:209], 0, s[96:97]
	s_addc_u32 s27, s27, 0
	s_add_i32 s28, s68, s9
	global_load_lds_dwordx4 v[180:181], off
	v_lshl_add_u64 v[180:181], s[26:27], 0, v[158:159]
	s_mov_b32 m0, s28
	v_lshl_add_u64 v[170:171], v[170:171], 0, s[96:97]
	global_load_lds_dwordx4 v[180:181], off
	v_lshl_add_u64 v[180:181], s[26:27], 0, v[142:143]
	s_add_i32 m0, s28, 0x2000
	s_nop 0
	global_load_lds_dwordx4 v[180:181], off
	v_lshl_add_u64 v[180:181], v[248:249], 0, s[96:97]
	s_mov_b32 m0, s0
	s_nop 0
	global_load_lds_dwordx4 v[180:181], off
	s_mov_b32 m0, s34
	s_nop 0
	global_load_lds_dwordx4 v[170:171], off
	s_waitcnt vmcnt(8)
	s_waitcnt lgkmcnt(0)
	s_setprio 1
	s_barrier
	v_mfma_f32_16x16x32_bf16 v[54:57], v[122:125], v[204:207], v[54:57]
	v_mfma_f32_16x16x32_bf16 v[62:65], v[130:133], v[204:207], v[62:65]
	v_mfma_f32_16x16x32_bf16 v[38:41], v[122:125], v[224:227], v[38:41]
	v_mfma_f32_16x16x32_bf16 v[50:53], v[130:133], v[224:227], v[50:53]
	v_mfma_f32_16x16x32_bf16 v[22:25], v[122:125], v[232:235], v[22:25]
	v_mfma_f32_16x16x32_bf16 v[34:37], v[130:133], v[232:235], v[34:37]
	v_mfma_f32_16x16x32_bf16 v[6:9], v[122:125], v[240:243], v[6:9]
	v_mfma_f32_16x16x32_bf16 v[18:21], v[130:133], v[240:243], v[18:21]
	v_mfma_f32_16x16x32_bf16 v[54:57], v[126:129], v[220:223], v[54:57]
	v_mfma_f32_16x16x32_bf16 v[62:65], v[172:175], v[220:223], v[62:65]
	v_mfma_f32_16x16x32_bf16 v[38:41], v[126:129], v[228:231], v[38:41]
	v_mfma_f32_16x16x32_bf16 v[50:53], v[172:175], v[228:231], v[50:53]
	v_mfma_f32_16x16x32_bf16 v[22:25], v[126:129], v[236:239], v[22:25]
	v_mfma_f32_16x16x32_bf16 v[34:37], v[172:175], v[236:239], v[34:37]
	v_mfma_f32_16x16x32_bf16 v[6:9], v[126:129], v[244:247], v[6:9]
	v_mfma_f32_16x16x32_bf16 v[18:21], v[172:175], v[244:247], v[18:21]
	v_mfma_f32_16x16x32_bf16 v[58:61], v[176:179], v[204:207], v[58:61]
	v_mfma_f32_16x16x32_bf16 v[46:49], v[196:199], v[204:207], v[46:49]
	v_mfma_f32_16x16x32_bf16 v[42:45], v[176:179], v[224:227], v[42:45]
	v_mfma_f32_16x16x32_bf16 v[30:33], v[196:199], v[224:227], v[30:33]
	v_mfma_f32_16x16x32_bf16 v[26:29], v[176:179], v[232:235], v[26:29]
	v_mfma_f32_16x16x32_bf16 v[14:17], v[196:199], v[232:235], v[14:17]
	v_mfma_f32_16x16x32_bf16 v[10:13], v[176:179], v[240:243], v[10:13]
	v_mfma_f32_16x16x32_bf16 v[2:5], v[196:199], v[240:243], v[2:5]
	v_mfma_f32_16x16x32_bf16 v[58:61], v[192:195], v[220:223], v[58:61]
	v_mfma_f32_16x16x32_bf16 v[46:49], v[200:203], v[220:223], v[46:49]
	v_mfma_f32_16x16x32_bf16 v[42:45], v[192:195], v[228:231], v[42:45]
	v_mfma_f32_16x16x32_bf16 v[30:33], v[200:203], v[228:231], v[30:33]
	v_mfma_f32_16x16x32_bf16 v[26:29], v[192:195], v[236:239], v[26:29]
	v_mfma_f32_16x16x32_bf16 v[14:17], v[200:203], v[236:239], v[14:17]
	v_mfma_f32_16x16x32_bf16 v[10:13], v[192:195], v[244:247], v[10:13]
	v_mfma_f32_16x16x32_bf16 v[2:5], v[200:203], v[244:247], v[2:5]
	s_barrier
	s_setprio 0
	s_add_i32 s17, s17, 2
	s_add_u32 vcc_lo, vcc_lo, 0x100
	s_addc_u32 s16, s16, 0
	s_add_u32 s62, s62, 0x100
	s_addc_u32 s63, s63, 0
	s_cmp_gt_u32 s17, 61
	s_cbranch_scc1 .Lpeel_exit_0

; #define PG8_BAR __builtin_amdgcn_s_barrier()
; template <class Epi, class Sched, bool ALIGN_EPI = false, bool SP2 = false>
; __device__ __forceinline__ void gemm_phase(PG8_LAS unsigned char* lds, const Gemm g, const Sched& S, const Epi& E) {
;     ...
;         if constexpr (ALIGN_EPI) { if (wr == 0) PG8_BAR; }
;         if constexpr (!Epi::AFTER_DRAIN) { E(acc, cur, wr, wc, fr, fq); S.done(cur); }
.Lpeel_exit_0:
	s_and_b64 vcc, exec, s[46:47]
	s_cbranch_vccz .LBB0_127
	s_barrier

;     __host__ __device__ bool next(int i, Unit& u) const { return at((long)i * G + c, u); }
; #define PG8_STAGE(bufoff, gbase, voff) do { _Pragma("unroll") for (int _i = 0; _i < 2; ++_i) \
;         __builtin_amdgcn_global_load_lds((const unsigned*)((const char*)(gbase) + (voff)[_i]), (PG8_LAS unsigned*)(lds + (bufoff) + ldsw + _i * 8192), 16, 0, 0); } while (0)
; #define PG8_LDA(dst, b, h) do { _Pragma("unroll") for (int m = 0; m < 4; ++m) _Pragma("unroll") for (int k = 0; k < 2; ++k) dst[m][k] = *(const PG8_LAS bf16x8*)(lds + PG8_SA(b, h) + aoff + m * 2048 + k * 1024); } while (0)
; #define PG8_LDB(dst, b, h) do { _Pragma("unroll") for (int n = 0; n < 2; ++n) _Pragma("unroll") for (int k = 0; k < 2; ++k) dst[n][k] = *(const PG8_LAS bf16x8*)(lds + PG8_SB(b, h) + boff + n * 2048 + k * 1024); } while (0)
; #define PG8_WAIT_V(n) asm volatile("s_waitcnt vmcnt(" #n ")" ::: "memory")
; #define PG8_BAR __builtin_amdgcn_s_barrier()
; template <class Epi, class Sched, bool ALIGN_EPI = false, bool SP2 = false>
; __device__ __forceinline__ void gemm_phase(PG8_LAS unsigned char* lds, const Gemm g, const Sched& S, const Epi& E) {
;     ...
;         const bool has_next = S.next(ui + 1, nxt);
;         const char* nA = has_next ? (const char*)g.A + (size_t)nxt.pm * tstep + (size_t)nxt.k0 * kstep : cA; const char* nB = has_next ? (const char*)g.Bt + (size_t)nxt.pn * tstep + (size_t)nxt.k0 * kstep : cB;
;         const int nt = cur.nt;
;         for (int t = 0; t < nt; t += 2) {
;             const bool last = (t == nt - 2);
;             const char* a1 = cA + (size_t)(t + 1) * kstep;
;             const char* a2 = last ? nA : cA + (size_t)(t + 2) * kstep; const char* b2 = last ? nB : cB + (size_t)(t + 2) * kstep;
;             const char* a3 = a2 + kstep; const char* b3 = b2 + kstep;
;             if (last && has_next) S.a_ready(nxt);
;             if constexpr (SP2) {
;             PG8_LDB(B0, 0, 0); PG8_LDB(B1, 0, 1); PG8_SCHED; PG8_LDA(At, 0, 0); PG8_STAGE(PG8_SA(1, 1), a1 + hstep, voffA);
;             PG8_WAIT_V(8); PG8_WAIT_L(0); PG8_BAR; PG8_MMA(0, 0, At, B0); PG8_MMA(0, 1, At, B1); PG8_BAR; PG8_SCHED;
;             PG8_LDA(At, 0, 1); PG8_STAGE(PG8_SB(0, 0), b2, voffB); PG8_STAGE(PG8_SB(0, 1), b2 + hstep, voffB); PG8_STAGE(PG8_SA(0, 0), a2, voffA);
;             PG8_WAIT_V(8); PG8_WAIT_L(0); PG8_BAR; PG8_MMA(1, 0, At, B0); PG8_MMA(1, 1, At, B1); PG8_BAR; PG8_SCHED;
.LBB0_418:
	s_ashr_i32 s41, s40, 31
	s_lshl_b64 s[16:17], s[40:41], 20
	s_add_u32 s44, s20, s16
	s_addc_u32 s45, s21, s17
	s_and_b64 s[16:17], s[42:43], exec
	s_cselect_b32 s15, s45, s29
	s_cselect_b32 s30, s44, s28
	s_ashr_i32 s39, s38, 31
	s_lshl_b64 s[16:17], s[38:39], 20
	s_add_u32 s46, s0, s16
	s_addc_u32 s47, s4, s17
	s_and_b64 s[16:17], s[42:43], exec
	s_cselect_b32 s31, s47, s27
	s_cselect_b32 s34, s46, s26
	s_add_u32 s35, s26, 0x100
	s_addc_u32 s16, s27, 0
	s_add_u32 s48, s28, 0x80080
	s_addc_u32 s49, s29, 0
	s_mov_b32 s17, -2
	s_waitcnt vmcnt(0)
	s_waitcnt vmcnt(0)
	s_add_u32 s26, s48, 0xfff80080
	s_addc_u32 s27, s49, -1
	s_add_i32 s39, 0, 0x10000
	s_cmp_eq_u32 s17, 28
	s_cselect_b32 s29, s15, s27
	s_cselect_b32 s28, s30, s26
	s_cselect_b32 s27, s31, s16
	s_cselect_b32 s26, s34, s35
	s_add_i32 s41, 0, 0x14000
	v_add_u32_e32 v142, s39, v190
	v_add_u32_e32 v170, s41, v190
	ds_read_b128 v[130:133], v142
	ds_read_b128 v[134:137], v142 offset:1024
	ds_read_b128 v[138:141], v142 offset:2048
	ds_read_b128 v[142:145], v142 offset:3072
	ds_read_b128 v[146:149], v170
	ds_read_b128 v[150:153], v170 offset:1024
	ds_read_b128 v[178:181], v170 offset:2048
	ds_read_b128 v[182:185], v170 offset:3072
	v_lshl_add_u64 v[170:171], s[48:49], 0, v[176:177]
	s_add_i32 m0, s6, 0xc000
	ds_read_b128 v[186:189], v192
	ds_read_b128 v[194:197], v192 offset:1024
	ds_read_b128 v[198:201], v192 offset:2048
	ds_read_b128 v[202:205], v192 offset:3072
	ds_read_b128 v[206:209], v192 offset:4096
	ds_read_b128 v[220:223], v192 offset:5120
	ds_read_b128 v[224:227], v192 offset:6144
	ds_read_b128 v[228:231], v192 offset:7168
	global_load_lds_dwordx4 v[170:171], off
	v_lshl_add_u64 v[170:171], s[48:49], 0, v[174:175]
	s_add_i32 m0, s6, 0xe000
	s_nop 0
	global_load_lds_dwordx4 v[170:171], off
	s_waitcnt vmcnt(8)
	s_waitcnt lgkmcnt(0)
	s_setprio 1
	s_barrier
	v_mfma_f32_16x16x32_bf16 v[126:129], v[130:133], v[186:189], 0
	v_mfma_f32_16x16x32_bf16 v[122:125], v[138:141], v[186:189], 0
	v_mfma_f32_16x16x32_bf16 v[110:113], v[130:133], v[198:201], 0
	v_mfma_f32_16x16x32_bf16 v[106:109], v[138:141], v[198:201], 0
	v_mfma_f32_16x16x32_bf16 v[94:97], v[130:133], v[206:209], 0
	v_mfma_f32_16x16x32_bf16 v[90:93], v[138:141], v[206:209], 0
	v_mfma_f32_16x16x32_bf16 v[78:81], v[130:133], v[224:227], 0
	v_mfma_f32_16x16x32_bf16 v[74:77], v[138:141], v[224:227], 0
	v_mfma_f32_16x16x32_bf16 v[126:129], v[134:137], v[194:197], v[126:129]
	v_mfma_f32_16x16x32_bf16 v[122:125], v[142:145], v[194:197], v[122:125]
	v_mfma_f32_16x16x32_bf16 v[110:113], v[134:137], v[202:205], v[110:113]
	v_mfma_f32_16x16x32_bf16 v[106:109], v[142:145], v[202:205], v[106:109]
	v_mfma_f32_16x16x32_bf16 v[94:97], v[134:137], v[220:223], v[94:97]
	v_mfma_f32_16x16x32_bf16 v[90:93], v[142:145], v[220:223], v[90:93]
	v_mfma_f32_16x16x32_bf16 v[78:81], v[134:137], v[228:231], v[78:81]
	v_mfma_f32_16x16x32_bf16 v[74:77], v[142:145], v[228:231], v[74:77]
	v_mfma_f32_16x16x32_bf16 v[118:121], v[146:149], v[186:189], 0
	v_mfma_f32_16x16x32_bf16 v[114:117], v[178:181], v[186:189], 0
	v_mfma_f32_16x16x32_bf16 v[102:105], v[146:149], v[198:201], 0
	v_mfma_f32_16x16x32_bf16 v[98:101], v[178:181], v[198:201], 0
	v_mfma_f32_16x16x32_bf16 v[86:89], v[146:149], v[206:209], 0
	v_mfma_f32_16x16x32_bf16 v[82:85], v[178:181], v[206:209], 0
	v_mfma_f32_16x16x32_bf16 v[70:73], v[146:149], v[224:227], 0
	v_mfma_f32_16x16x32_bf16 v[66:69], v[178:181], v[224:227], 0
	v_mfma_f32_16x16x32_bf16 v[118:121], v[150:153], v[194:197], v[118:121]
	v_mfma_f32_16x16x32_bf16 v[114:117], v[182:185], v[194:197], v[114:117]
	v_mfma_f32_16x16x32_bf16 v[102:105], v[150:153], v[202:205], v[102:105]
	v_mfma_f32_16x16x32_bf16 v[98:101], v[182:185], v[202:205], v[98:101]
	v_mfma_f32_16x16x32_bf16 v[86:89], v[150:153], v[220:223], v[86:89]
	v_mfma_f32_16x16x32_bf16 v[82:85], v[182:185], v[220:223], v[82:85]
	v_mfma_f32_16x16x32_bf16 v[70:73], v[150:153], v[228:231], v[70:73]
	v_mfma_f32_16x16x32_bf16 v[66:69], v[182:185], v[228:231], v[66:69]
	s_barrier
	s_setprio 0
	s_add_i32 s39, s39, s5
	v_lshl_add_u64 v[170:171], s[26:27], 0, v[158:159]
	s_mov_b32 m0, s39
	ds_read_b128 v[186:189], v192 offset:16384
	ds_read_b128 v[194:197], v192 offset:17408
	ds_read_b128 v[198:201], v192 offset:18432
	ds_read_b128 v[202:205], v192 offset:19456
	ds_read_b128 v[206:209], v192 offset:20480
	ds_read_b128 v[220:223], v192 offset:21504
	ds_read_b128 v[224:227], v192 offset:22528
	ds_read_b128 v[228:231], v192 offset:23552
	global_load_lds_dwordx4 v[170:171], off
	s_add_i32 m0, s39, 0x2000
	s_add_u32 s50, s26, 0x80000
	v_lshl_add_u64 v[210:211], s[26:27], 0, v[154:155]
	s_addc_u32 s51, s27, 0
	s_add_i32 s39, s41, s5
	global_load_lds_dwordx4 v[210:211], off
	v_lshl_add_u64 v[232:233], s[50:51], 0, v[158:159]
	s_mov_b32 m0, s39
	v_lshl_add_u64 v[234:235], s[28:29], 0, v[156:157]
	global_load_lds_dwordx4 v[232:233], off
	v_lshl_add_u64 v[232:233], s[50:51], 0, v[154:155]
	s_add_i32 m0, s39, 0x2000
	s_nop 0
	global_load_lds_dwordx4 v[232:233], off
	v_lshl_add_u64 v[232:233], s[28:29], 0, v[172:173]
	s_mov_b32 m0, s6
	s_nop 0
	global_load_lds_dwordx4 v[232:233], off
	s_mov_b32 m0, s7
	s_nop 0
	global_load_lds_dwordx4 v[234:235], off
	s_waitcnt vmcnt(8)
	s_waitcnt lgkmcnt(0)
	s_setprio 1
	s_barrier
; #define PG8_STAGE(bufoff, gbase, voff) do { _Pragma("unroll") for (int _i = 0; _i < 2; ++_i) \
;         __builtin_amdgcn_global_load_lds((const unsigned*)((const char*)(gbase) + (voff)[_i]), (PG8_LAS unsigned*)(lds + (bufoff) + ldsw + _i * 8192), 16, 0, 0); } while (0)
; #define PG8_LDA(dst, b, h) do { _Pragma("unroll") for (int m = 0; m < 4; ++m) _Pragma("unroll") for (int k = 0; k < 2; ++k) dst[m][k] = *(const PG8_LAS bf16x8*)(lds + PG8_SA(b, h) + aoff + m * 2048 + k * 1024); } while (0)
; #define PG8_LDB(dst, b, h) do { _Pragma("unroll") for (int n = 0; n < 2; ++n) _Pragma("unroll") for (int k = 0; k < 2; ++k) dst[n][k] = *(const PG8_LAS bf16x8*)(lds + PG8_SB(b, h) + boff + n * 2048 + k * 1024); } while (0)
; #define PG8_MMA(ai, bj, At, Bt) do { __builtin_amdgcn_s_setprio(1); _Pragma("unroll") for (int m = 0; m < 4; ++m) _Pragma("unroll") for (int n = 0; n < 2; ++n) _Pragma("unroll") for (int k = 0; k < 2; ++k) \
;         acc[ai][bj][m][n] = __builtin_amdgcn_mfma_f32_16x16x32_bf16(Bt[n][k], At[m][k], acc[ai][bj][m][n], 0, 0, 0); __builtin_amdgcn_s_setprio(0); } while (0)
; #define PG8_WAIT_V(n) asm volatile("s_waitcnt vmcnt(" #n ")" ::: "memory")
; #define PG8_WAIT_L(n) asm volatile("s_waitcnt lgkmcnt(" #n ")" ::: "memory")
; #define PG8_BAR __builtin_amdgcn_s_barrier()
; #define PG8_SCHED __builtin_amdgcn_sched_barrier(0)
; template <class Epi, class Sched, bool ALIGN_EPI = false, bool SP2 = false>
; __device__ __forceinline__ void gemm_phase(PG8_LAS unsigned char* lds, const Gemm g, const Sched& S, const Epi& E) {
;     ...
;             PG8_WAIT_V(8); PG8_WAIT_L(0); PG8_BAR; PG8_MMA(1, 0, At, B0); PG8_MMA(1, 1, At, B1); PG8_BAR; PG8_SCHED;
;             PG8_LDB(B0, 1, 0); PG8_LDB(B1, 1, 1); PG8_SCHED; PG8_LDA(At, 1, 0); PG8_STAGE(PG8_SA(0, 1), a2 + hstep, voffA);
;             PG8_WAIT_V(8); PG8_WAIT_L(0); PG8_BAR; PG8_MMA(0, 0, At, B0); PG8_MMA(0, 1, At, B1); PG8_BAR; PG8_SCHED;
	v_mfma_f32_16x16x32_bf16 v[62:65], v[130:133], v[186:189], 0
	v_mfma_f32_16x16x32_bf16 v[58:61], v[138:141], v[186:189], 0
	v_mfma_f32_16x16x32_bf16 v[46:49], v[130:133], v[198:201], 0
	v_mfma_f32_16x16x32_bf16 v[42:45], v[138:141], v[198:201], 0
	v_mfma_f32_16x16x32_bf16 v[30:33], v[130:133], v[206:209], 0
	v_mfma_f32_16x16x32_bf16 v[26:29], v[138:141], v[206:209], 0
	v_mfma_f32_16x16x32_bf16 v[14:17], v[130:133], v[224:227], 0
	v_mfma_f32_16x16x32_bf16 v[10:13], v[138:141], v[224:227], 0
	v_mfma_f32_16x16x32_bf16 v[62:65], v[134:137], v[194:197], v[62:65]
	v_mfma_f32_16x16x32_bf16 v[58:61], v[142:145], v[194:197], v[58:61]
	v_mfma_f32_16x16x32_bf16 v[46:49], v[134:137], v[202:205], v[46:49]
	v_mfma_f32_16x16x32_bf16 v[42:45], v[142:145], v[202:205], v[42:45]
	v_mfma_f32_16x16x32_bf16 v[30:33], v[134:137], v[220:223], v[30:33]
	v_mfma_f32_16x16x32_bf16 v[26:29], v[142:145], v[220:223], v[26:29]
	v_mfma_f32_16x16x32_bf16 v[14:17], v[134:137], v[228:231], v[14:17]
	v_mfma_f32_16x16x32_bf16 v[10:13], v[142:145], v[228:231], v[10:13]
	v_mfma_f32_16x16x32_bf16 v[54:57], v[146:149], v[186:189], 0
	v_mfma_f32_16x16x32_bf16 v[50:53], v[178:181], v[186:189], 0
	v_mfma_f32_16x16x32_bf16 v[38:41], v[146:149], v[198:201], 0
	v_mfma_f32_16x16x32_bf16 v[34:37], v[178:181], v[198:201], 0
	v_mfma_f32_16x16x32_bf16 v[22:25], v[146:149], v[206:209], 0
	v_mfma_f32_16x16x32_bf16 v[18:21], v[178:181], v[206:209], 0
	v_mfma_f32_16x16x32_bf16 v[6:9], v[146:149], v[224:227], 0
	v_mfma_f32_16x16x32_bf16 v[2:5], v[178:181], v[224:227], 0
	v_mfma_f32_16x16x32_bf16 v[54:57], v[150:153], v[194:197], v[54:57]
	v_mfma_f32_16x16x32_bf16 v[50:53], v[182:185], v[194:197], v[50:53]
	v_mfma_f32_16x16x32_bf16 v[38:41], v[150:153], v[202:205], v[38:41]
	v_mfma_f32_16x16x32_bf16 v[34:37], v[182:185], v[202:205], v[34:37]
	v_mfma_f32_16x16x32_bf16 v[22:25], v[150:153], v[220:223], v[22:25]
	v_mfma_f32_16x16x32_bf16 v[18:21], v[182:185], v[220:223], v[18:21]
	v_mfma_f32_16x16x32_bf16 v[6:9], v[150:153], v[228:231], v[6:9]
	v_mfma_f32_16x16x32_bf16 v[2:5], v[182:185], v[228:231], v[2:5]
	s_barrier
	s_setprio 0
	s_add_i32 s39, 0, 0x18000
	s_add_i32 s41, 0, 0x1c000
	v_add_u32_e32 v142, s39, v190
	v_add_u32_e32 v182, s41, v190
	ds_read_b128 v[130:133], v142
	ds_read_b128 v[134:137], v142 offset:1024
	ds_read_b128 v[138:141], v142 offset:2048
	ds_read_b128 v[142:145], v142 offset:3072
	ds_read_b128 v[146:149], v182
	ds_read_b128 v[150:153], v182 offset:1024
	ds_read_b128 v[178:181], v182 offset:2048
	ds_read_b128 v[182:185], v182 offset:3072
	s_add_u32 s28, s28, 0x80000
	s_addc_u32 s29, s29, 0
	s_mov_b32 m0, s8
	v_lshl_add_u64 v[236:237], s[28:29], 0, v[172:173]
	ds_read_b128 v[186:189], v192 offset:32768
	ds_read_b128 v[194:197], v192 offset:33792
	ds_read_b128 v[198:201], v192 offset:34816
	ds_read_b128 v[202:205], v192 offset:35840
	ds_read_b128 v[206:209], v192 offset:36864
	ds_read_b128 v[220:223], v192 offset:37888
	ds_read_b128 v[224:227], v192 offset:38912
	ds_read_b128 v[228:231], v192 offset:39936
	global_load_lds_dwordx4 v[236:237], off
	v_lshl_add_u64 v[236:237], s[28:29], 0, v[156:157]
	s_mov_b32 m0, s9
	s_nop 0
	global_load_lds_dwordx4 v[236:237], off
	s_waitcnt vmcnt(8)
	s_waitcnt lgkmcnt(0)
	s_setprio 1
	s_barrier
	v_mfma_f32_16x16x32_bf16 v[126:129], v[130:133], v[186:189], v[126:129]
	v_mfma_f32_16x16x32_bf16 v[122:125], v[138:141], v[186:189], v[122:125]
	v_mfma_f32_16x16x32_bf16 v[110:113], v[130:133], v[198:201], v[110:113]
	v_mfma_f32_16x16x32_bf16 v[106:109], v[138:141], v[198:201], v[106:109]
	v_mfma_f32_16x16x32_bf16 v[94:97], v[130:133], v[206:209], v[94:97]
	v_mfma_f32_16x16x32_bf16 v[90:93], v[138:141], v[206:209], v[90:93]
	v_mfma_f32_16x16x32_bf16 v[78:81], v[130:133], v[224:227], v[78:81]
	v_mfma_f32_16x16x32_bf16 v[74:77], v[138:141], v[224:227], v[74:77]
	v_mfma_f32_16x16x32_bf16 v[126:129], v[134:137], v[194:197], v[126:129]
	v_mfma_f32_16x16x32_bf16 v[122:125], v[142:145], v[194:197], v[122:125]
	v_mfma_f32_16x16x32_bf16 v[110:113], v[134:137], v[202:205], v[110:113]
	v_mfma_f32_16x16x32_bf16 v[106:109], v[142:145], v[202:205], v[106:109]
	v_mfma_f32_16x16x32_bf16 v[94:97], v[134:137], v[220:223], v[94:97]
	v_mfma_f32_16x16x32_bf16 v[90:93], v[142:145], v[220:223], v[90:93]
	v_mfma_f32_16x16x32_bf16 v[78:81], v[134:137], v[228:231], v[78:81]
	v_mfma_f32_16x16x32_bf16 v[74:77], v[142:145], v[228:231], v[74:77]
	v_mfma_f32_16x16x32_bf16 v[118:121], v[146:149], v[186:189], v[118:121]
	v_mfma_f32_16x16x32_bf16 v[114:117], v[178:181], v[186:189], v[114:117]
	v_mfma_f32_16x16x32_bf16 v[102:105], v[146:149], v[198:201], v[102:105]
	v_mfma_f32_16x16x32_bf16 v[98:101], v[178:181], v[198:201], v[98:101]
	v_mfma_f32_16x16x32_bf16 v[86:89], v[146:149], v[206:209], v[86:89]
	v_mfma_f32_16x16x32_bf16 v[82:85], v[178:181], v[206:209], v[82:85]
	v_mfma_f32_16x16x32_bf16 v[70:73], v[146:149], v[224:227], v[70:73]
	v_mfma_f32_16x16x32_bf16 v[66:69], v[178:181], v[224:227], v[66:69]
	v_mfma_f32_16x16x32_bf16 v[118:121], v[150:153], v[194:197], v[118:121]
	v_mfma_f32_16x16x32_bf16 v[114:117], v[182:185], v[194:197], v[114:117]
	v_mfma_f32_16x16x32_bf16 v[102:105], v[150:153], v[202:205], v[102:105]
	v_mfma_f32_16x16x32_bf16 v[98:101], v[182:185], v[202:205], v[98:101]
	v_mfma_f32_16x16x32_bf16 v[86:89], v[150:153], v[220:223], v[86:89]
	v_mfma_f32_16x16x32_bf16 v[82:85], v[182:185], v[220:223], v[82:85]
	v_mfma_f32_16x16x32_bf16 v[70:73], v[150:153], v[228:231], v[70:73]
	v_mfma_f32_16x16x32_bf16 v[66:69], v[182:185], v[228:231], v[66:69]
	s_barrier
; #define PG8_STAGE(bufoff, gbase, voff) do { _Pragma("unroll") for (int _i = 0; _i < 2; ++_i) \
;         __builtin_amdgcn_global_load_lds((const unsigned*)((const char*)(gbase) + (voff)[_i]), (PG8_LAS unsigned*)(lds + (bufoff) + ldsw + _i * 8192), 16, 0, 0); } while (0)
; #define PG8_LDA(dst, b, h) do { _Pragma("unroll") for (int m = 0; m < 4; ++m) _Pragma("unroll") for (int k = 0; k < 2; ++k) dst[m][k] = *(const PG8_LAS bf16x8*)(lds + PG8_SA(b, h) + aoff + m * 2048 + k * 1024); } while (0)
; #define PG8_LDB(dst, b, h) do { _Pragma("unroll") for (int n = 0; n < 2; ++n) _Pragma("unroll") for (int k = 0; k < 2; ++k) dst[n][k] = *(const PG8_LAS bf16x8*)(lds + PG8_SB(b, h) + boff + n * 2048 + k * 1024); } while (0)
; template <class Epi, class Sched, bool ALIGN_EPI = false, bool SP2 = false>
; __device__ __forceinline__ void gemm_phase(PG8_LAS unsigned char* lds, const Gemm g, const Sched& S, const Epi& E) {
;     ...
;         for (int t = 0; t < nt; t += 2) {
;             const bool last = (t == nt - 2);
;             const char* a1 = cA + (size_t)(t + 1) * kstep;
;             const char* a2 = last ? nA : cA + (size_t)(t + 2) * kstep; const char* b2 = last ? nB : cB + (size_t)(t + 2) * kstep;
;             const char* a3 = a2 + kstep; const char* b3 = b2 + kstep;
;             if (last && has_next) S.a_ready(nxt);
;             if constexpr (SP2) {
;             PG8_LDB(B0, 0, 0); PG8_LDB(B1, 0, 1); PG8_SCHED; PG8_LDA(At, 0, 0); PG8_STAGE(PG8_SA(1, 1), a1 + hstep, voffA);
;             PG8_WAIT_V(8); PG8_WAIT_L(0); PG8_BAR; PG8_MMA(0, 0, At, B0); PG8_MMA(0, 1, At, B1); PG8_BAR; PG8_SCHED;
;             PG8_LDA(At, 0, 1); PG8_STAGE(PG8_SB(0, 0), b2, voffB); PG8_STAGE(PG8_SB(0, 1), b2 + hstep, voffB); PG8_STAGE(PG8_SA(0, 0), a2, voffA);
;             PG8_WAIT_V(8); PG8_WAIT_L(0); PG8_BAR; PG8_MMA(1, 0, At, B0); PG8_MMA(1, 1, At, B1); PG8_BAR; PG8_SCHED;
;             PG8_LDB(B0, 1, 0); PG8_LDB(B1, 1, 1); PG8_SCHED; PG8_LDA(At, 1, 0); PG8_STAGE(PG8_SA(0, 1), a2 + hstep, voffA);
;             PG8_WAIT_V(8); PG8_WAIT_L(0); PG8_BAR; PG8_MMA(0, 0, At, B0); PG8_MMA(0, 1, At, B1); PG8_BAR; PG8_SCHED;
;             PG8_LDA(At, 1, 1); PG8_STAGE(PG8_SB(1, 0), b3, voffB); PG8_STAGE(PG8_SB(1, 1), b3 + hstep, voffB); PG8_STAGE(PG8_SA(1, 0), a3, voffA);
;             PG8_WAIT_V(8); PG8_WAIT_L(0); PG8_BAR; PG8_MMA(1, 0, At, B0); PG8_MMA(1, 1, At, B1); PG8_BAR; PG8_SCHED;
	s_setprio 0
	s_add_i32 s28, s39, s5
	v_lshl_add_u64 v[170:171], v[170:171], 0, s[96:97]
	s_mov_b32 m0, s28
	ds_read_b128 v[186:189], v192 offset:49152
	ds_read_b128 v[194:197], v192 offset:50176
	ds_read_b128 v[198:201], v192 offset:51200
	ds_read_b128 v[202:205], v192 offset:52224
	ds_read_b128 v[206:209], v192 offset:53248
	ds_read_b128 v[220:223], v192 offset:54272
	ds_read_b128 v[224:227], v192 offset:55296
	ds_read_b128 v[228:231], v192 offset:56320
	global_load_lds_dwordx4 v[170:171], off
	s_add_i32 m0, s28, 0x2000
	s_add_u32 s26, s26, 0x80080
	v_lshl_add_u64 v[170:171], v[210:211], 0, s[96:97]
	s_addc_u32 s27, s27, 0
	s_add_i32 s28, s41, s5
	global_load_lds_dwordx4 v[170:171], off
	v_lshl_add_u64 v[170:171], s[26:27], 0, v[158:159]
	s_mov_b32 m0, s28
	s_nop 0
	global_load_lds_dwordx4 v[170:171], off
	v_lshl_add_u64 v[170:171], s[26:27], 0, v[154:155]
	s_add_i32 m0, s28, 0x2000
	s_nop 0
	global_load_lds_dwordx4 v[170:171], off
	v_lshl_add_u64 v[170:171], v[232:233], 0, s[96:97]
	s_mov_b32 m0, s10
	s_nop 0
	global_load_lds_dwordx4 v[170:171], off
	v_lshl_add_u64 v[170:171], v[234:235], 0, s[96:97]
	s_mov_b32 m0, s11
	s_nop 0
	global_load_lds_dwordx4 v[170:171], off
	s_waitcnt vmcnt(8)
	s_waitcnt lgkmcnt(0)
	s_setprio 1
	s_barrier
	v_mfma_f32_16x16x32_bf16 v[62:65], v[130:133], v[186:189], v[62:65]
	v_mfma_f32_16x16x32_bf16 v[58:61], v[138:141], v[186:189], v[58:61]
	v_mfma_f32_16x16x32_bf16 v[46:49], v[130:133], v[198:201], v[46:49]
	v_mfma_f32_16x16x32_bf16 v[42:45], v[138:141], v[198:201], v[42:45]
	v_mfma_f32_16x16x32_bf16 v[30:33], v[130:133], v[206:209], v[30:33]
	v_mfma_f32_16x16x32_bf16 v[26:29], v[138:141], v[206:209], v[26:29]
	v_mfma_f32_16x16x32_bf16 v[14:17], v[130:133], v[224:227], v[14:17]
	v_mfma_f32_16x16x32_bf16 v[10:13], v[138:141], v[224:227], v[10:13]
	v_mfma_f32_16x16x32_bf16 v[62:65], v[134:137], v[194:197], v[62:65]
	v_mfma_f32_16x16x32_bf16 v[58:61], v[142:145], v[194:197], v[58:61]
	v_mfma_f32_16x16x32_bf16 v[46:49], v[134:137], v[202:205], v[46:49]
	v_mfma_f32_16x16x32_bf16 v[42:45], v[142:145], v[202:205], v[42:45]
	v_mfma_f32_16x16x32_bf16 v[30:33], v[134:137], v[220:223], v[30:33]
	v_mfma_f32_16x16x32_bf16 v[26:29], v[142:145], v[220:223], v[26:29]
	v_mfma_f32_16x16x32_bf16 v[14:17], v[134:137], v[228:231], v[14:17]
	v_mfma_f32_16x16x32_bf16 v[10:13], v[142:145], v[228:231], v[10:13]
	v_mfma_f32_16x16x32_bf16 v[54:57], v[146:149], v[186:189], v[54:57]
	v_mfma_f32_16x16x32_bf16 v[50:53], v[178:181], v[186:189], v[50:53]
	v_mfma_f32_16x16x32_bf16 v[38:41], v[146:149], v[198:201], v[38:41]
	v_mfma_f32_16x16x32_bf16 v[34:37], v[178:181], v[198:201], v[34:37]
	v_mfma_f32_16x16x32_bf16 v[22:25], v[146:149], v[206:209], v[22:25]
	v_mfma_f32_16x16x32_bf16 v[18:21], v[178:181], v[206:209], v[18:21]
	v_mfma_f32_16x16x32_bf16 v[6:9], v[146:149], v[224:227], v[6:9]
	v_mfma_f32_16x16x32_bf16 v[2:5], v[178:181], v[224:227], v[2:5]
	v_mfma_f32_16x16x32_bf16 v[54:57], v[150:153], v[194:197], v[54:57]
	v_mfma_f32_16x16x32_bf16 v[50:53], v[182:185], v[194:197], v[50:53]
	v_mfma_f32_16x16x32_bf16 v[38:41], v[150:153], v[202:205], v[38:41]
	v_mfma_f32_16x16x32_bf16 v[34:37], v[182:185], v[202:205], v[34:37]
	v_mfma_f32_16x16x32_bf16 v[22:25], v[150:153], v[220:223], v[22:25]
	v_mfma_f32_16x16x32_bf16 v[18:21], v[182:185], v[220:223], v[18:21]
	v_mfma_f32_16x16x32_bf16 v[6:9], v[150:153], v[228:231], v[6:9]
	v_mfma_f32_16x16x32_bf16 v[2:5], v[182:185], v[228:231], v[2:5]
	s_barrier
	s_setprio 0
	s_add_i32 s17, s17, 2
	s_add_u32 s35, s35, 0x100
	s_addc_u32 s16, s16, 0
	s_add_u32 s48, s48, 0x100
	s_addc_u32 s49, s49, 0
	s_cmp_gt_u32 s17, 29
	s_cbranch_scc1 .Lpeel_exit_1

; #define PG8_BAR __builtin_amdgcn_s_barrier()
; template <class Epi, class Sched, bool ALIGN_EPI = false, bool SP2 = false>
; __device__ __forceinline__ void gemm_phase(PG8_LAS unsigned char* lds, const Gemm g, const Sched& S, const Epi& E) {
;     ...
;         if constexpr (ALIGN_EPI) { if (wr == 0) PG8_BAR; }
;         if constexpr (!Epi::AFTER_DRAIN) { E(acc, cur, wr, wc, fr, fq); S.done(cur); }
.Lpeel_exit_1:
	s_and_b64 vcc, exec, s[36:37]
	s_cbranch_vccz .LBB0_422
	s_barrier

;     __host__ __device__ bool next(int i, Unit& u) const { return at((long)i * G + c, u); }
; #define PG8_STAGE(bufoff, gbase, voff) do { _Pragma("unroll") for (int _i = 0; _i < 2; ++_i) \
;         __builtin_amdgcn_global_load_lds((const unsigned*)((const char*)(gbase) + (voff)[_i]), (PG8_LAS unsigned*)(lds + (bufoff) + ldsw + _i * 8192), 16, 0, 0); } while (0)
; #define PG8_LDA(dst, b, h) do { _Pragma("unroll") for (int m = 0; m < 4; ++m) _Pragma("unroll") for (int k = 0; k < 2; ++k) dst[m][k] = *(const PG8_LAS bf16x8*)(lds + PG8_SA(b, h) + aoff + m * 2048 + k * 1024); } while (0)
; #define PG8_LDB(dst, b, h) do { _Pragma("unroll") for (int n = 0; n < 2; ++n) _Pragma("unroll") for (int k = 0; k < 2; ++k) dst[n][k] = *(const PG8_LAS bf16x8*)(lds + PG8_SB(b, h) + boff + n * 2048 + k * 1024); } while (0)
; #define PG8_WAIT_V(n) asm volatile("s_waitcnt vmcnt(" #n ")" ::: "memory")
; #define PG8_BAR __builtin_amdgcn_s_barrier()
; template <class Epi, class Sched, bool ALIGN_EPI = false, bool SP2 = false>
; __device__ __forceinline__ void gemm_phase(PG8_LAS unsigned char* lds, const Gemm g, const Sched& S, const Epi& E) {
;     ...
;         const bool has_next = S.next(ui + 1, nxt);
;         const char* nA = has_next ? (const char*)g.A + (size_t)nxt.pm * tstep + (size_t)nxt.k0 * kstep : cA; const char* nB = has_next ? (const char*)g.Bt + (size_t)nxt.pn * tstep + (size_t)nxt.k0 * kstep : cB;
;         const int nt = cur.nt;
;         for (int t = 0; t < nt; t += 2) {
;             const bool last = (t == nt - 2);
;             const char* a1 = cA + (size_t)(t + 1) * kstep;
;             const char* a2 = last ? nA : cA + (size_t)(t + 2) * kstep; const char* b2 = last ? nB : cB + (size_t)(t + 2) * kstep;
;             const char* a3 = a2 + kstep; const char* b3 = b2 + kstep;
;             if (last && has_next) S.a_ready(nxt);
;             if constexpr (SP2) {
;             PG8_LDB(B0, 0, 0); PG8_LDB(B1, 0, 1); PG8_SCHED; PG8_LDA(At, 0, 0); PG8_STAGE(PG8_SA(1, 1), a1 + hstep, voffA);
;             PG8_WAIT_V(8); PG8_WAIT_L(0); PG8_BAR; PG8_MMA(0, 0, At, B0); PG8_MMA(0, 1, At, B1); PG8_BAR; PG8_SCHED;
;             PG8_LDA(At, 0, 1); PG8_STAGE(PG8_SB(0, 0), b2, voffB); PG8_STAGE(PG8_SB(0, 1), b2 + hstep, voffB); PG8_STAGE(PG8_SA(0, 0), a2, voffA);
;             PG8_WAIT_V(8); PG8_WAIT_L(0); PG8_BAR; PG8_MMA(1, 0, At, B0); PG8_MMA(1, 1, At, B1); PG8_BAR; PG8_SCHED;
.LBB0_529:
	s_add_i32 s14, s13, -2
	s_add_u32 s15, s58, 0x100
	s_addc_u32 s16, s59, 0
	s_add_u32 s24, s24, 0x100080
	s_addc_u32 s25, s25, 0
	s_mov_b32 s17, 0
	s_waitcnt vmcnt(0)
	s_waitcnt vmcnt(0)
	s_add_i32 s21, s17, 2
	s_add_u32 s23, s24, 0xfff00080
	s_addc_u32 s26, s25, -1
	s_add_i32 s30, 0, 0x10000
	s_cmp_eq_u32 s14, s17
	s_cselect_b32 s29, s55, s26
	s_cselect_b32 s28, s54, s23
	s_cselect_b32 s27, s57, s16
	s_cselect_b32 s26, s56, s15
	s_add_i32 s17, 0, 0x14000
	v_add_u32_e32 v142, s30, v190
	v_add_u32_e32 v170, s17, v190
	ds_read_b128 v[130:133], v142
	ds_read_b128 v[134:137], v142 offset:1024
	ds_read_b128 v[138:141], v142 offset:2048
	ds_read_b128 v[142:145], v142 offset:3072
	ds_read_b128 v[146:149], v170
	ds_read_b128 v[150:153], v170 offset:1024
	ds_read_b128 v[178:181], v170 offset:2048
	ds_read_b128 v[182:185], v170 offset:3072
	v_lshl_add_u64 v[170:171], s[24:25], 0, v[176:177]
	s_add_i32 m0, s35, 0xc000
	ds_read_b128 v[186:189], v192
	ds_read_b128 v[194:197], v192 offset:1024
	ds_read_b128 v[198:201], v192 offset:2048
	ds_read_b128 v[202:205], v192 offset:3072
	ds_read_b128 v[206:209], v192 offset:4096
	ds_read_b128 v[220:223], v192 offset:5120
	ds_read_b128 v[224:227], v192 offset:6144
	ds_read_b128 v[228:231], v192 offset:7168
	global_load_lds_dwordx4 v[170:171], off
	v_lshl_add_u64 v[170:171], s[24:25], 0, v[174:175]
	s_add_i32 m0, s35, 0xe000
	s_nop 0
	global_load_lds_dwordx4 v[170:171], off
	s_waitcnt vmcnt(8)
	s_waitcnt lgkmcnt(0)
	s_setprio 1
	s_barrier
	v_mfma_f32_16x16x32_bf16 v[126:129], v[130:133], v[186:189], 0
	v_mfma_f32_16x16x32_bf16 v[122:125], v[138:141], v[186:189], 0
	v_mfma_f32_16x16x32_bf16 v[118:121], v[130:133], v[198:201], 0
	v_mfma_f32_16x16x32_bf16 v[114:117], v[138:141], v[198:201], 0
	v_mfma_f32_16x16x32_bf16 v[102:105], v[130:133], v[206:209], 0
	v_mfma_f32_16x16x32_bf16 v[94:97], v[138:141], v[206:209], 0
	v_mfma_f32_16x16x32_bf16 v[86:89], v[130:133], v[224:227], 0
	v_mfma_f32_16x16x32_bf16 v[78:81], v[138:141], v[224:227], 0
	v_mfma_f32_16x16x32_bf16 v[126:129], v[134:137], v[194:197], v[126:129]
	v_mfma_f32_16x16x32_bf16 v[122:125], v[142:145], v[194:197], v[122:125]
	v_mfma_f32_16x16x32_bf16 v[118:121], v[134:137], v[202:205], v[118:121]
	v_mfma_f32_16x16x32_bf16 v[114:117], v[142:145], v[202:205], v[114:117]
	v_mfma_f32_16x16x32_bf16 v[102:105], v[134:137], v[220:223], v[102:105]
	v_mfma_f32_16x16x32_bf16 v[94:97], v[142:145], v[220:223], v[94:97]
	v_mfma_f32_16x16x32_bf16 v[86:89], v[134:137], v[228:231], v[86:89]
	v_mfma_f32_16x16x32_bf16 v[78:81], v[142:145], v[228:231], v[78:81]
	v_mfma_f32_16x16x32_bf16 v[110:113], v[146:149], v[186:189], 0
	v_mfma_f32_16x16x32_bf16 v[106:109], v[178:181], v[186:189], 0
	v_mfma_f32_16x16x32_bf16 v[98:101], v[146:149], v[198:201], 0
	v_mfma_f32_16x16x32_bf16 v[90:93], v[178:181], v[198:201], 0
	v_mfma_f32_16x16x32_bf16 v[82:85], v[146:149], v[206:209], 0
	v_mfma_f32_16x16x32_bf16 v[74:77], v[178:181], v[206:209], 0
	v_mfma_f32_16x16x32_bf16 v[70:73], v[146:149], v[224:227], 0
	v_mfma_f32_16x16x32_bf16 v[66:69], v[178:181], v[224:227], 0
	v_mfma_f32_16x16x32_bf16 v[110:113], v[150:153], v[194:197], v[110:113]
	v_mfma_f32_16x16x32_bf16 v[106:109], v[182:185], v[194:197], v[106:109]
	v_mfma_f32_16x16x32_bf16 v[98:101], v[150:153], v[202:205], v[98:101]
	v_mfma_f32_16x16x32_bf16 v[90:93], v[182:185], v[202:205], v[90:93]
	v_mfma_f32_16x16x32_bf16 v[82:85], v[150:153], v[220:223], v[82:85]
	v_mfma_f32_16x16x32_bf16 v[74:77], v[182:185], v[220:223], v[74:77]
	v_mfma_f32_16x16x32_bf16 v[70:73], v[150:153], v[228:231], v[70:73]
	v_mfma_f32_16x16x32_bf16 v[66:69], v[182:185], v[228:231], v[66:69]
	s_barrier
	s_setprio 0
	s_add_i32 s23, s30, s34
	v_lshl_add_u64 v[170:171], s[26:27], 0, v[158:159]
	s_mov_b32 m0, s23
	ds_read_b128 v[186:189], v192 offset:16384
	ds_read_b128 v[194:197], v192 offset:17408
	ds_read_b128 v[198:201], v192 offset:18432
	ds_read_b128 v[202:205], v192 offset:19456
	ds_read_b128 v[206:209], v192 offset:20480
	ds_read_b128 v[220:223], v192 offset:21504
	ds_read_b128 v[224:227], v192 offset:22528
	ds_read_b128 v[228:231], v192 offset:23552
	global_load_lds_dwordx4 v[170:171], off
	s_add_i32 m0, s23, 0x2000
	s_add_u32 s58, s26, 0x100000
	v_lshl_add_u64 v[210:211], s[26:27], 0, v[172:173]
	s_addc_u32 s59, s27, 0
	s_add_i32 s17, s17, s34
	global_load_lds_dwordx4 v[210:211], off
	v_lshl_add_u64 v[232:233], s[58:59], 0, v[158:159]
	s_mov_b32 m0, s17
	v_lshl_add_u64 v[234:235], s[28:29], 0, v[156:157]
	global_load_lds_dwordx4 v[232:233], off
	v_lshl_add_u64 v[232:233], s[58:59], 0, v[172:173]
	s_add_i32 m0, s17, 0x2000
	s_nop 0
	global_load_lds_dwordx4 v[232:233], off
	v_lshl_add_u64 v[232:233], s[28:29], 0, v[154:155]
	s_mov_b32 m0, s35
	s_nop 0
	global_load_lds_dwordx4 v[232:233], off
	s_mov_b32 m0, s4
	s_nop 0
	global_load_lds_dwordx4 v[234:235], off
	s_waitcnt vmcnt(8)
	s_waitcnt lgkmcnt(0)
	s_setprio 1
	s_barrier
; #define PG8_STAGE(bufoff, gbase, voff) do { _Pragma("unroll") for (int _i = 0; _i < 2; ++_i) \
;         __builtin_amdgcn_global_load_lds((const unsigned*)((const char*)(gbase) + (voff)[_i]), (PG8_LAS unsigned*)(lds + (bufoff) + ldsw + _i * 8192), 16, 0, 0); } while (0)
; #define PG8_LDA(dst, b, h) do { _Pragma("unroll") for (int m = 0; m < 4; ++m) _Pragma("unroll") for (int k = 0; k < 2; ++k) dst[m][k] = *(const PG8_LAS bf16x8*)(lds + PG8_SA(b, h) + aoff + m * 2048 + k * 1024); } while (0)
; #define PG8_LDB(dst, b, h) do { _Pragma("unroll") for (int n = 0; n < 2; ++n) _Pragma("unroll") for (int k = 0; k < 2; ++k) dst[n][k] = *(const PG8_LAS bf16x8*)(lds + PG8_SB(b, h) + boff + n * 2048 + k * 1024); } while (0)
; #define PG8_MMA(ai, bj, At, Bt) do { __builtin_amdgcn_s_setprio(1); _Pragma("unroll") for (int m = 0; m < 4; ++m) _Pragma("unroll") for (int n = 0; n < 2; ++n) _Pragma("unroll") for (int k = 0; k < 2; ++k) \
;         acc[ai][bj][m][n] = __builtin_amdgcn_mfma_f32_16x16x32_bf16(Bt[n][k], At[m][k], acc[ai][bj][m][n], 0, 0, 0); __builtin_amdgcn_s_setprio(0); } while (0)
; #define PG8_WAIT_V(n) asm volatile("s_waitcnt vmcnt(" #n ")" ::: "memory")
; #define PG8_WAIT_L(n) asm volatile("s_waitcnt lgkmcnt(" #n ")" ::: "memory")
; #define PG8_BAR __builtin_amdgcn_s_barrier()
; #define PG8_SCHED __builtin_amdgcn_sched_barrier(0)
; template <class Epi, class Sched, bool ALIGN_EPI = false, bool SP2 = false>
; __device__ __forceinline__ void gemm_phase(PG8_LAS unsigned char* lds, const Gemm g, const Sched& S, const Epi& E) {
;     ...
;             PG8_WAIT_V(8); PG8_WAIT_L(0); PG8_BAR; PG8_MMA(1, 0, At, B0); PG8_MMA(1, 1, At, B1); PG8_BAR; PG8_SCHED;
;             PG8_LDB(B0, 1, 0); PG8_LDB(B1, 1, 1); PG8_SCHED; PG8_LDA(At, 1, 0); PG8_STAGE(PG8_SA(0, 1), a2 + hstep, voffA);
;             PG8_WAIT_V(8); PG8_WAIT_L(0); PG8_BAR; PG8_MMA(0, 0, At, B0); PG8_MMA(0, 1, At, B1); PG8_BAR; PG8_SCHED;
	v_mfma_f32_16x16x32_bf16 v[62:65], v[130:133], v[186:189], 0
	v_mfma_f32_16x16x32_bf16 v[58:61], v[138:141], v[186:189], 0
	v_mfma_f32_16x16x32_bf16 v[54:57], v[130:133], v[198:201], 0
	v_mfma_f32_16x16x32_bf16 v[46:49], v[138:141], v[198:201], 0
	v_mfma_f32_16x16x32_bf16 v[38:41], v[130:133], v[206:209], 0
	v_mfma_f32_16x16x32_bf16 v[30:33], v[138:141], v[206:209], 0
	v_mfma_f32_16x16x32_bf16 v[22:25], v[130:133], v[224:227], 0
	v_mfma_f32_16x16x32_bf16 v[14:17], v[138:141], v[224:227], 0
	v_mfma_f32_16x16x32_bf16 v[62:65], v[134:137], v[194:197], v[62:65]
	v_mfma_f32_16x16x32_bf16 v[58:61], v[142:145], v[194:197], v[58:61]
	v_mfma_f32_16x16x32_bf16 v[54:57], v[134:137], v[202:205], v[54:57]
	v_mfma_f32_16x16x32_bf16 v[46:49], v[142:145], v[202:205], v[46:49]
	v_mfma_f32_16x16x32_bf16 v[38:41], v[134:137], v[220:223], v[38:41]
	v_mfma_f32_16x16x32_bf16 v[30:33], v[142:145], v[220:223], v[30:33]
	v_mfma_f32_16x16x32_bf16 v[22:25], v[134:137], v[228:231], v[22:25]
	v_mfma_f32_16x16x32_bf16 v[14:17], v[142:145], v[228:231], v[14:17]
	v_mfma_f32_16x16x32_bf16 v[50:53], v[146:149], v[186:189], 0
	v_mfma_f32_16x16x32_bf16 v[42:45], v[178:181], v[186:189], 0
	v_mfma_f32_16x16x32_bf16 v[34:37], v[146:149], v[198:201], 0
	v_mfma_f32_16x16x32_bf16 v[26:29], v[178:181], v[198:201], 0
	v_mfma_f32_16x16x32_bf16 v[18:21], v[146:149], v[206:209], 0
	v_mfma_f32_16x16x32_bf16 v[10:13], v[178:181], v[206:209], 0
	v_mfma_f32_16x16x32_bf16 v[6:9], v[146:149], v[224:227], 0
	v_mfma_f32_16x16x32_bf16 v[2:5], v[178:181], v[224:227], 0
	v_mfma_f32_16x16x32_bf16 v[50:53], v[150:153], v[194:197], v[50:53]
	v_mfma_f32_16x16x32_bf16 v[42:45], v[182:185], v[194:197], v[42:45]
	v_mfma_f32_16x16x32_bf16 v[34:37], v[150:153], v[202:205], v[34:37]
	v_mfma_f32_16x16x32_bf16 v[26:29], v[182:185], v[202:205], v[26:29]
	v_mfma_f32_16x16x32_bf16 v[18:21], v[150:153], v[220:223], v[18:21]
	v_mfma_f32_16x16x32_bf16 v[10:13], v[182:185], v[220:223], v[10:13]
	v_mfma_f32_16x16x32_bf16 v[6:9], v[150:153], v[228:231], v[6:9]
	v_mfma_f32_16x16x32_bf16 v[2:5], v[182:185], v[228:231], v[2:5]
	s_barrier
	s_setprio 0
	s_add_i32 s17, 0, 0x18000
	s_add_i32 s23, 0, 0x1c000
	v_add_u32_e32 v142, s17, v190
	v_add_u32_e32 v182, s23, v190
	ds_read_b128 v[130:133], v142
	ds_read_b128 v[134:137], v142 offset:1024
	ds_read_b128 v[138:141], v142 offset:2048
	ds_read_b128 v[142:145], v142 offset:3072
	ds_read_b128 v[146:149], v182
	ds_read_b128 v[150:153], v182 offset:1024
	ds_read_b128 v[178:181], v182 offset:2048
	ds_read_b128 v[182:185], v182 offset:3072
	s_add_u32 s28, s28, 0x100000
	s_addc_u32 s29, s29, 0
	s_mov_b32 m0, s5
	v_lshl_add_u64 v[236:237], s[28:29], 0, v[154:155]
	ds_read_b128 v[186:189], v192 offset:32768
	ds_read_b128 v[194:197], v192 offset:33792
	ds_read_b128 v[198:201], v192 offset:34816
	ds_read_b128 v[202:205], v192 offset:35840
	ds_read_b128 v[206:209], v192 offset:36864
	ds_read_b128 v[220:223], v192 offset:37888
	ds_read_b128 v[224:227], v192 offset:38912
	ds_read_b128 v[228:231], v192 offset:39936
	global_load_lds_dwordx4 v[236:237], off
	v_lshl_add_u64 v[236:237], s[28:29], 0, v[156:157]
	s_mov_b32 m0, s6
	s_nop 0
	global_load_lds_dwordx4 v[236:237], off
	s_waitcnt vmcnt(8)
	s_waitcnt lgkmcnt(0)
	s_setprio 1
	s_barrier
	v_mfma_f32_16x16x32_bf16 v[126:129], v[130:133], v[186:189], v[126:129]
	v_mfma_f32_16x16x32_bf16 v[122:125], v[138:141], v[186:189], v[122:125]
	v_mfma_f32_16x16x32_bf16 v[118:121], v[130:133], v[198:201], v[118:121]
	v_mfma_f32_16x16x32_bf16 v[114:117], v[138:141], v[198:201], v[114:117]
	v_mfma_f32_16x16x32_bf16 v[102:105], v[130:133], v[206:209], v[102:105]
	v_mfma_f32_16x16x32_bf16 v[94:97], v[138:141], v[206:209], v[94:97]
	v_mfma_f32_16x16x32_bf16 v[86:89], v[130:133], v[224:227], v[86:89]
	v_mfma_f32_16x16x32_bf16 v[78:81], v[138:141], v[224:227], v[78:81]
	v_mfma_f32_16x16x32_bf16 v[126:129], v[134:137], v[194:197], v[126:129]
	v_mfma_f32_16x16x32_bf16 v[122:125], v[142:145], v[194:197], v[122:125]
	v_mfma_f32_16x16x32_bf16 v[118:121], v[134:137], v[202:205], v[118:121]
	v_mfma_f32_16x16x32_bf16 v[114:117], v[142:145], v[202:205], v[114:117]
	v_mfma_f32_16x16x32_bf16 v[102:105], v[134:137], v[220:223], v[102:105]
	v_mfma_f32_16x16x32_bf16 v[94:97], v[142:145], v[220:223], v[94:97]
	v_mfma_f32_16x16x32_bf16 v[86:89], v[134:137], v[228:231], v[86:89]
	v_mfma_f32_16x16x32_bf16 v[78:81], v[142:145], v[228:231], v[78:81]
	v_mfma_f32_16x16x32_bf16 v[110:113], v[146:149], v[186:189], v[110:113]
	v_mfma_f32_16x16x32_bf16 v[106:109], v[178:181], v[186:189], v[106:109]
	v_mfma_f32_16x16x32_bf16 v[98:101], v[146:149], v[198:201], v[98:101]
	v_mfma_f32_16x16x32_bf16 v[90:93], v[178:181], v[198:201], v[90:93]
	v_mfma_f32_16x16x32_bf16 v[82:85], v[146:149], v[206:209], v[82:85]
	v_mfma_f32_16x16x32_bf16 v[74:77], v[178:181], v[206:209], v[74:77]
	v_mfma_f32_16x16x32_bf16 v[70:73], v[146:149], v[224:227], v[70:73]
	v_mfma_f32_16x16x32_bf16 v[66:69], v[178:181], v[224:227], v[66:69]
	v_mfma_f32_16x16x32_bf16 v[110:113], v[150:153], v[194:197], v[110:113]
	v_mfma_f32_16x16x32_bf16 v[106:109], v[182:185], v[194:197], v[106:109]
	v_mfma_f32_16x16x32_bf16 v[98:101], v[150:153], v[202:205], v[98:101]
	v_mfma_f32_16x16x32_bf16 v[90:93], v[182:185], v[202:205], v[90:93]
	v_mfma_f32_16x16x32_bf16 v[82:85], v[150:153], v[220:223], v[82:85]
	v_mfma_f32_16x16x32_bf16 v[74:77], v[182:185], v[220:223], v[74:77]
	v_mfma_f32_16x16x32_bf16 v[70:73], v[150:153], v[228:231], v[70:73]
	v_mfma_f32_16x16x32_bf16 v[66:69], v[182:185], v[228:231], v[66:69]
	s_barrier
; #define PG8_STAGE(bufoff, gbase, voff) do { _Pragma("unroll") for (int _i = 0; _i < 2; ++_i) \
;         __builtin_amdgcn_global_load_lds((const unsigned*)((const char*)(gbase) + (voff)[_i]), (PG8_LAS unsigned*)(lds + (bufoff) + ldsw + _i * 8192), 16, 0, 0); } while (0)
; #define PG8_LDA(dst, b, h) do { _Pragma("unroll") for (int m = 0; m < 4; ++m) _Pragma("unroll") for (int k = 0; k < 2; ++k) dst[m][k] = *(const PG8_LAS bf16x8*)(lds + PG8_SA(b, h) + aoff + m * 2048 + k * 1024); } while (0)
; #define PG8_LDB(dst, b, h) do { _Pragma("unroll") for (int n = 0; n < 2; ++n) _Pragma("unroll") for (int k = 0; k < 2; ++k) dst[n][k] = *(const PG8_LAS bf16x8*)(lds + PG8_SB(b, h) + boff + n * 2048 + k * 1024); } while (0)
; template <class Epi, class Sched, bool ALIGN_EPI = false, bool SP2 = false>
; __device__ __forceinline__ void gemm_phase(PG8_LAS unsigned char* lds, const Gemm g, const Sched& S, const Epi& E) {
;     ...
;         for (int t = 0; t < nt; t += 2) {
;             const bool last = (t == nt - 2);
;             const char* a1 = cA + (size_t)(t + 1) * kstep;
;             const char* a2 = last ? nA : cA + (size_t)(t + 2) * kstep; const char* b2 = last ? nB : cB + (size_t)(t + 2) * kstep;
;             const char* a3 = a2 + kstep; const char* b3 = b2 + kstep;
;             if (last && has_next) S.a_ready(nxt);
;             if constexpr (SP2) {
;             PG8_LDB(B0, 0, 0); PG8_LDB(B1, 0, 1); PG8_SCHED; PG8_LDA(At, 0, 0); PG8_STAGE(PG8_SA(1, 1), a1 + hstep, voffA);
;             PG8_WAIT_V(8); PG8_WAIT_L(0); PG8_BAR; PG8_MMA(0, 0, At, B0); PG8_MMA(0, 1, At, B1); PG8_BAR; PG8_SCHED;
;             PG8_LDA(At, 0, 1); PG8_STAGE(PG8_SB(0, 0), b2, voffB); PG8_STAGE(PG8_SB(0, 1), b2 + hstep, voffB); PG8_STAGE(PG8_SA(0, 0), a2, voffA);
;             PG8_WAIT_V(8); PG8_WAIT_L(0); PG8_BAR; PG8_MMA(1, 0, At, B0); PG8_MMA(1, 1, At, B1); PG8_BAR; PG8_SCHED;
;             PG8_LDB(B0, 1, 0); PG8_LDB(B1, 1, 1); PG8_SCHED; PG8_LDA(At, 1, 0); PG8_STAGE(PG8_SA(0, 1), a2 + hstep, voffA);
;             PG8_WAIT_V(8); PG8_WAIT_L(0); PG8_BAR; PG8_MMA(0, 0, At, B0); PG8_MMA(0, 1, At, B1); PG8_BAR; PG8_SCHED;
;             PG8_LDA(At, 1, 1); PG8_STAGE(PG8_SB(1, 0), b3, voffB); PG8_STAGE(PG8_SB(1, 1), b3 + hstep, voffB); PG8_STAGE(PG8_SA(1, 0), a3, voffA);
;             PG8_WAIT_V(8); PG8_WAIT_L(0); PG8_BAR; PG8_MMA(1, 0, At, B0); PG8_MMA(1, 1, At, B1); PG8_BAR; PG8_SCHED;
	s_setprio 0
	s_add_i32 s17, s17, s34
	v_lshl_add_u64 v[170:171], v[170:171], 0, s[96:97]
	s_mov_b32 m0, s17
	ds_read_b128 v[186:189], v192 offset:49152
	ds_read_b128 v[194:197], v192 offset:50176
	ds_read_b128 v[198:201], v192 offset:51200
	ds_read_b128 v[202:205], v192 offset:52224
	ds_read_b128 v[206:209], v192 offset:53248
	ds_read_b128 v[220:223], v192 offset:54272
	ds_read_b128 v[224:227], v192 offset:55296
	ds_read_b128 v[228:231], v192 offset:56320
	global_load_lds_dwordx4 v[170:171], off
	s_add_i32 m0, s17, 0x2000
	s_add_u32 s26, s26, 0x100080
	v_lshl_add_u64 v[170:171], v[210:211], 0, s[96:97]
	s_addc_u32 s27, s27, 0
	s_add_i32 s17, s23, s34
	global_load_lds_dwordx4 v[170:171], off
	v_lshl_add_u64 v[170:171], s[26:27], 0, v[158:159]
	s_mov_b32 m0, s17
	s_nop 0
	global_load_lds_dwordx4 v[170:171], off
	v_lshl_add_u64 v[170:171], s[26:27], 0, v[172:173]
	s_add_i32 m0, s17, 0x2000
	s_nop 0
	global_load_lds_dwordx4 v[170:171], off
	v_lshl_add_u64 v[170:171], v[232:233], 0, s[96:97]
	s_mov_b32 m0, s9
	s_nop 0
	global_load_lds_dwordx4 v[170:171], off
	v_lshl_add_u64 v[170:171], v[234:235], 0, s[96:97]
	s_mov_b32 m0, s10
	s_nop 0
	global_load_lds_dwordx4 v[170:171], off
	s_waitcnt vmcnt(8)
	s_waitcnt lgkmcnt(0)
	s_setprio 1
	s_barrier
	v_mfma_f32_16x16x32_bf16 v[62:65], v[130:133], v[186:189], v[62:65]
	v_mfma_f32_16x16x32_bf16 v[58:61], v[138:141], v[186:189], v[58:61]
	v_mfma_f32_16x16x32_bf16 v[54:57], v[130:133], v[198:201], v[54:57]
	v_mfma_f32_16x16x32_bf16 v[46:49], v[138:141], v[198:201], v[46:49]
	v_mfma_f32_16x16x32_bf16 v[38:41], v[130:133], v[206:209], v[38:41]
	v_mfma_f32_16x16x32_bf16 v[30:33], v[138:141], v[206:209], v[30:33]
	v_mfma_f32_16x16x32_bf16 v[22:25], v[130:133], v[224:227], v[22:25]
	v_mfma_f32_16x16x32_bf16 v[14:17], v[138:141], v[224:227], v[14:17]
	v_mfma_f32_16x16x32_bf16 v[62:65], v[134:137], v[194:197], v[62:65]
	v_mfma_f32_16x16x32_bf16 v[58:61], v[142:145], v[194:197], v[58:61]
	v_mfma_f32_16x16x32_bf16 v[54:57], v[134:137], v[202:205], v[54:57]
	v_mfma_f32_16x16x32_bf16 v[46:49], v[142:145], v[202:205], v[46:49]
	v_mfma_f32_16x16x32_bf16 v[38:41], v[134:137], v[220:223], v[38:41]
	v_mfma_f32_16x16x32_bf16 v[30:33], v[142:145], v[220:223], v[30:33]
	v_mfma_f32_16x16x32_bf16 v[22:25], v[134:137], v[228:231], v[22:25]
	v_mfma_f32_16x16x32_bf16 v[14:17], v[142:145], v[228:231], v[14:17]
	v_mfma_f32_16x16x32_bf16 v[50:53], v[146:149], v[186:189], v[50:53]
	v_mfma_f32_16x16x32_bf16 v[42:45], v[178:181], v[186:189], v[42:45]
	v_mfma_f32_16x16x32_bf16 v[34:37], v[146:149], v[198:201], v[34:37]
	v_mfma_f32_16x16x32_bf16 v[26:29], v[178:181], v[198:201], v[26:29]
	v_mfma_f32_16x16x32_bf16 v[18:21], v[146:149], v[206:209], v[18:21]
	v_mfma_f32_16x16x32_bf16 v[10:13], v[178:181], v[206:209], v[10:13]
	v_mfma_f32_16x16x32_bf16 v[6:9], v[146:149], v[224:227], v[6:9]
	v_mfma_f32_16x16x32_bf16 v[2:5], v[178:181], v[224:227], v[2:5]
	v_mfma_f32_16x16x32_bf16 v[50:53], v[150:153], v[194:197], v[50:53]
	v_mfma_f32_16x16x32_bf16 v[42:45], v[182:185], v[194:197], v[42:45]
	v_mfma_f32_16x16x32_bf16 v[34:37], v[150:153], v[202:205], v[34:37]
	v_mfma_f32_16x16x32_bf16 v[26:29], v[182:185], v[202:205], v[26:29]
	v_mfma_f32_16x16x32_bf16 v[18:21], v[150:153], v[220:223], v[18:21]
	v_mfma_f32_16x16x32_bf16 v[10:13], v[182:185], v[220:223], v[10:13]
	v_mfma_f32_16x16x32_bf16 v[6:9], v[150:153], v[228:231], v[6:9]
	v_mfma_f32_16x16x32_bf16 v[2:5], v[182:185], v[228:231], v[2:5]
	s_barrier
	s_setprio 0
	s_add_u32 s15, s15, 0x100
	s_addc_u32 s16, s16, 0
	s_add_u32 s24, s24, 0x100
	s_addc_u32 s25, s25, 0
	s_cmp_ge_i32 s21, s13
	s_mov_b32 s17, s21
	s_cbranch_scc1 .Lpeel_exit_2

;     __host__ __device__ bool next(int i, Unit& u) const { return at((long)i * G + c, u); }
; #define PG8_STAGE(bufoff, gbase, voff) do { _Pragma("unroll") for (int _i = 0; _i < 2; ++_i) \
;         __builtin_amdgcn_global_load_lds((const unsigned*)((const char*)(gbase) + (voff)[_i]), (PG8_LAS unsigned*)(lds + (bufoff) + ldsw + _i * 8192), 16, 0, 0); } while (0)
; #define PG8_LDA(dst, b, h) do { _Pragma("unroll") for (int m = 0; m < 4; ++m) _Pragma("unroll") for (int k = 0; k < 2; ++k) dst[m][k] = *(const PG8_LAS bf16x8*)(lds + PG8_SA(b, h) + aoff + m * 2048 + k * 1024); } while (0)
; #define PG8_LDB(dst, b, h) do { _Pragma("unroll") for (int n = 0; n < 2; ++n) _Pragma("unroll") for (int k = 0; k < 2; ++k) dst[n][k] = *(const PG8_LAS bf16x8*)(lds + PG8_SB(b, h) + boff + n * 2048 + k * 1024); } while (0)
; #define PG8_WAIT_V(n) asm volatile("s_waitcnt vmcnt(" #n ")" ::: "memory")
; #define PG8_BAR __builtin_amdgcn_s_barrier()
; template <class Epi, class Sched, bool ALIGN_EPI = false, bool SP2 = false>
; __device__ __forceinline__ void gemm_phase(PG8_LAS unsigned char* lds, const Gemm g, const Sched& S, const Epi& E) {
;     ...
;         const bool has_next = S.next(ui + 1, nxt);
;         const char* nA = has_next ? (const char*)g.A + (size_t)nxt.pm * tstep + (size_t)nxt.k0 * kstep : cA; const char* nB = has_next ? (const char*)g.Bt + (size_t)nxt.pn * tstep + (size_t)nxt.k0 * kstep : cB;
;         const int nt = cur.nt;
;         for (int t = 0; t < nt; t += 2) {
;             const bool last = (t == nt - 2);
;             const char* a1 = cA + (size_t)(t + 1) * kstep;
;             const char* a2 = last ? nA : cA + (size_t)(t + 2) * kstep; const char* b2 = last ? nB : cB + (size_t)(t + 2) * kstep;
;             const char* a3 = a2 + kstep; const char* b3 = b2 + kstep;
;             if (last && has_next) S.a_ready(nxt);
;             if constexpr (SP2) {
;             PG8_LDB(B0, 0, 0); PG8_LDB(B1, 0, 1); PG8_SCHED; PG8_LDA(At, 0, 0); PG8_STAGE(PG8_SA(1, 1), a1 + hstep, voffA);
;             PG8_WAIT_V(8); PG8_WAIT_L(0); PG8_BAR; PG8_MMA(0, 0, At, B0); PG8_MMA(0, 1, At, B1); PG8_BAR; PG8_SCHED;
;             PG8_LDA(At, 0, 1); PG8_STAGE(PG8_SB(0, 0), b2, voffB); PG8_STAGE(PG8_SB(0, 1), b2 + hstep, voffB); PG8_STAGE(PG8_SA(0, 0), a2, voffA);
;             PG8_WAIT_V(8); PG8_WAIT_L(0); PG8_BAR; PG8_MMA(1, 0, At, B0); PG8_MMA(1, 1, At, B1); PG8_BAR; PG8_SCHED;
.LBB0_709:
	s_ashr_i32 s63, s62, 31
	s_lshl_b64 s[16:17], s[62:63], 21
	s_add_u32 s28, s4, s16
	s_addc_u32 s29, s5, s17
	s_and_b64 s[16:17], s[20:21], exec
	s_cselect_b32 s30, s29, s23
	s_cselect_b32 s31, s28, s22
	s_ashr_i32 s61, s60, 31
	s_lshl_b64 s[16:17], s[60:61], 21
	s_add_u32 s26, s6, s16
	s_addc_u32 s27, s7, s17
	s_and_b64 s[16:17], s[20:21], exec
	s_cselect_b32 s61, s27, s25
	s_cselect_b32 s63, s26, s24
	s_add_u32 s16, s24, 0x100
	s_addc_u32 s17, s25, 0
	s_add_u32 vcc_lo, s22, 0x100080
	s_addc_u32 vcc_hi, s23, 0
	s_mov_b32 s65, -2
	s_waitcnt vmcnt(0)
	s_add_u32 s22, vcc_lo, 0xfff00080
	s_addc_u32 s23, vcc_hi, -1
	s_add_i32 s68, 0, 0x10000
	s_cmp_eq_u32 s65, 60
	s_cselect_b32 s25, s30, s23
	s_cselect_b32 s24, s31, s22
	s_cselect_b32 s23, s61, s17
	s_cselect_b32 s22, s63, s16
	s_add_i32 s70, 0, 0x14000
	v_add_u32_e32 v70, s68, v220
	v_add_u32_e32 v170, s70, v220
	ds_read_b128 v[50:53], v70
	ds_read_b128 v[54:57], v70 offset:1024
	ds_read_b128 v[66:69], v70 offset:2048
	ds_read_b128 v[70:73], v70 offset:3072
	ds_read_b128 v[74:77], v170
	ds_read_b128 v[86:89], v170 offset:1024
	ds_read_b128 v[154:157], v170 offset:2048
	ds_read_b128 v[188:191], v170 offset:3072
	v_lshl_add_u64 v[170:171], vcc, 0, v[186:187]
	s_add_i32 m0, s10, 0xc000
	ds_read_b128 v[192:195], v222
	ds_read_b128 v[196:199], v222 offset:1024
	ds_read_b128 v[200:203], v222 offset:2048
	ds_read_b128 v[204:207], v222 offset:3072
	ds_read_b128 v[224:227], v222 offset:4096
	ds_read_b128 v[228:231], v222 offset:5120
	ds_read_b128 v[232:235], v222 offset:6144
	ds_read_b128 v[236:239], v222 offset:7168
	global_load_lds_dwordx4 v[170:171], off
	v_lshl_add_u64 v[170:171], vcc, 0, v[184:185]
	s_add_i32 m0, s10, 0xe000
	s_nop 0
	global_load_lds_dwordx4 v[170:171], off
	s_waitcnt vmcnt(8)
	s_waitcnt lgkmcnt(0)
	s_setprio 1
	s_barrier
	v_mfma_f32_16x16x32_bf16 v[142:145], v[50:53], v[192:195], 0
	v_mfma_f32_16x16x32_bf16 v[130:133], v[66:69], v[192:195], 0
	v_mfma_f32_16x16x32_bf16 v[138:141], v[50:53], v[200:203], 0
	v_mfma_f32_16x16x32_bf16 v[126:129], v[66:69], v[200:203], 0
	v_mfma_f32_16x16x32_bf16 v[118:121], v[50:53], v[224:227], 0
	v_mfma_f32_16x16x32_bf16 v[110:113], v[66:69], v[224:227], 0
	v_mfma_f32_16x16x32_bf16 v[98:101], v[50:53], v[232:235], 0
	v_mfma_f32_16x16x32_bf16 v[94:97], v[66:69], v[232:235], 0
	v_mfma_f32_16x16x32_bf16 v[142:145], v[54:57], v[196:199], v[142:145]
	v_mfma_f32_16x16x32_bf16 v[130:133], v[70:73], v[196:199], v[130:133]
	v_mfma_f32_16x16x32_bf16 v[138:141], v[54:57], v[204:207], v[138:141]
	v_mfma_f32_16x16x32_bf16 v[126:129], v[70:73], v[204:207], v[126:129]
	v_mfma_f32_16x16x32_bf16 v[118:121], v[54:57], v[228:231], v[118:121]
	v_mfma_f32_16x16x32_bf16 v[110:113], v[70:73], v[228:231], v[110:113]
	v_mfma_f32_16x16x32_bf16 v[98:101], v[54:57], v[236:239], v[98:101]
	v_mfma_f32_16x16x32_bf16 v[94:97], v[70:73], v[236:239], v[94:97]
	v_mfma_f32_16x16x32_bf16 v[150:153], v[74:77], v[192:195], 0
	v_mfma_f32_16x16x32_bf16 v[146:149], v[154:157], v[192:195], 0
	v_mfma_f32_16x16x32_bf16 v[134:137], v[74:77], v[200:203], 0
	v_mfma_f32_16x16x32_bf16 v[122:125], v[154:157], v[200:203], 0
	v_mfma_f32_16x16x32_bf16 v[114:117], v[74:77], v[224:227], 0
	v_mfma_f32_16x16x32_bf16 v[106:109], v[154:157], v[224:227], 0
	v_mfma_f32_16x16x32_bf16 v[102:105], v[74:77], v[232:235], 0
	v_mfma_f32_16x16x32_bf16 v[90:93], v[154:157], v[232:235], 0
	v_mfma_f32_16x16x32_bf16 v[150:153], v[86:89], v[196:199], v[150:153]
	v_mfma_f32_16x16x32_bf16 v[146:149], v[188:191], v[196:199], v[146:149]
	v_mfma_f32_16x16x32_bf16 v[134:137], v[86:89], v[204:207], v[134:137]
	v_mfma_f32_16x16x32_bf16 v[122:125], v[188:191], v[204:207], v[122:125]
	v_mfma_f32_16x16x32_bf16 v[114:117], v[86:89], v[228:231], v[114:117]
	v_mfma_f32_16x16x32_bf16 v[106:109], v[188:191], v[228:231], v[106:109]
	v_mfma_f32_16x16x32_bf16 v[102:105], v[86:89], v[236:239], v[102:105]
	v_mfma_f32_16x16x32_bf16 v[90:93], v[188:191], v[236:239], v[90:93]
	s_barrier
	s_setprio 0
	s_add_i32 s68, s68, s9
	v_lshl_add_u64 v[170:171], s[22:23], 0, v[158:159]
	s_mov_b32 m0, s68
	ds_read_b128 v[192:195], v222 offset:16384
	ds_read_b128 v[196:199], v222 offset:17408
	ds_read_b128 v[200:203], v222 offset:18432
	ds_read_b128 v[204:207], v222 offset:19456
	ds_read_b128 v[224:227], v222 offset:20480
	ds_read_b128 v[228:231], v222 offset:21504
	ds_read_b128 v[232:235], v222 offset:22528
	ds_read_b128 v[236:239], v222 offset:23552
	global_load_lds_dwordx4 v[170:171], off
	s_add_i32 m0, s68, 0x2000
	s_add_u32 s68, s22, 0x100000
	v_lshl_add_u64 v[208:209], s[22:23], 0, v[172:173]
	s_addc_u32 s69, s23, 0
	s_add_i32 s70, s70, s9
	global_load_lds_dwordx4 v[208:209], off
	v_lshl_add_u64 v[210:211], s[68:69], 0, v[158:159]
	s_mov_b32 m0, s70
	v_lshl_add_u64 v[244:245], s[24:25], 0, v[174:175]
	global_load_lds_dwordx4 v[210:211], off
	v_lshl_add_u64 v[210:211], s[68:69], 0, v[172:173]
	s_add_i32 m0, s70, 0x2000
	s_nop 0
	global_load_lds_dwordx4 v[210:211], off
	v_lshl_add_u64 v[210:211], s[24:25], 0, v[176:177]
	s_mov_b32 m0, s10
	s_nop 0
	global_load_lds_dwordx4 v[210:211], off
	s_mov_b32 m0, s11
	s_nop 0
	global_load_lds_dwordx4 v[244:245], off
	s_waitcnt vmcnt(8)
	s_waitcnt lgkmcnt(0)
	s_setprio 1
	s_barrier
; #define PG8_STAGE(bufoff, gbase, voff) do { _Pragma("unroll") for (int _i = 0; _i < 2; ++_i) \
;         __builtin_amdgcn_global_load_lds((const unsigned*)((const char*)(gbase) + (voff)[_i]), (PG8_LAS unsigned*)(lds + (bufoff) + ldsw + _i * 8192), 16, 0, 0); } while (0)
; #define PG8_LDA(dst, b, h) do { _Pragma("unroll") for (int m = 0; m < 4; ++m) _Pragma("unroll") for (int k = 0; k < 2; ++k) dst[m][k] = *(const PG8_LAS bf16x8*)(lds + PG8_SA(b, h) + aoff + m * 2048 + k * 1024); } while (0)
; #define PG8_LDB(dst, b, h) do { _Pragma("unroll") for (int n = 0; n < 2; ++n) _Pragma("unroll") for (int k = 0; k < 2; ++k) dst[n][k] = *(const PG8_LAS bf16x8*)(lds + PG8_SB(b, h) + boff + n * 2048 + k * 1024); } while (0)
; #define PG8_MMA(ai, bj, At, Bt) do { __builtin_amdgcn_s_setprio(1); _Pragma("unroll") for (int m = 0; m < 4; ++m) _Pragma("unroll") for (int n = 0; n < 2; ++n) _Pragma("unroll") for (int k = 0; k < 2; ++k) \
;         acc[ai][bj][m][n] = __builtin_amdgcn_mfma_f32_16x16x32_bf16(Bt[n][k], At[m][k], acc[ai][bj][m][n], 0, 0, 0); __builtin_amdgcn_s_setprio(0); } while (0)
; #define PG8_WAIT_V(n) asm volatile("s_waitcnt vmcnt(" #n ")" ::: "memory")
; #define PG8_WAIT_L(n) asm volatile("s_waitcnt lgkmcnt(" #n ")" ::: "memory")
; #define PG8_BAR __builtin_amdgcn_s_barrier()
; #define PG8_SCHED __builtin_amdgcn_sched_barrier(0)
; template <class Epi, class Sched, bool ALIGN_EPI = false, bool SP2 = false>
; __device__ __forceinline__ void gemm_phase(PG8_LAS unsigned char* lds, const Gemm g, const Sched& S, const Epi& E) {
;     ...
;             PG8_WAIT_V(8); PG8_WAIT_L(0); PG8_BAR; PG8_MMA(1, 0, At, B0); PG8_MMA(1, 1, At, B1); PG8_BAR; PG8_SCHED;
;             PG8_LDB(B0, 1, 0); PG8_LDB(B1, 1, 1); PG8_SCHED; PG8_LDA(At, 1, 0); PG8_STAGE(PG8_SA(0, 1), a2 + hstep, voffA);
;             PG8_WAIT_V(8); PG8_WAIT_L(0); PG8_BAR; PG8_MMA(0, 0, At, B0); PG8_MMA(0, 1, At, B1); PG8_BAR; PG8_SCHED;
	v_mfma_f32_16x16x32_bf16 v[62:65], v[50:53], v[192:195], 0
	v_mfma_f32_16x16x32_bf16 v[42:45], v[66:69], v[192:195], 0
	v_mfma_f32_16x16x32_bf16 v[58:61], v[50:53], v[200:203], 0
	v_mfma_f32_16x16x32_bf16 v[38:41], v[66:69], v[200:203], 0
	v_mfma_f32_16x16x32_bf16 v[30:33], v[50:53], v[224:227], 0
	v_mfma_f32_16x16x32_bf16 v[22:25], v[66:69], v[224:227], 0
	v_mfma_f32_16x16x32_bf16 v[10:13], v[50:53], v[232:235], 0
	v_mfma_f32_16x16x32_bf16 v[6:9], v[66:69], v[232:235], 0
	v_mfma_f32_16x16x32_bf16 v[62:65], v[54:57], v[196:199], v[62:65]
	v_mfma_f32_16x16x32_bf16 v[42:45], v[70:73], v[196:199], v[42:45]
	v_mfma_f32_16x16x32_bf16 v[58:61], v[54:57], v[204:207], v[58:61]
	v_mfma_f32_16x16x32_bf16 v[38:41], v[70:73], v[204:207], v[38:41]
	v_mfma_f32_16x16x32_bf16 v[30:33], v[54:57], v[228:231], v[30:33]
	v_mfma_f32_16x16x32_bf16 v[22:25], v[70:73], v[228:231], v[22:25]
	v_mfma_f32_16x16x32_bf16 v[10:13], v[54:57], v[236:239], v[10:13]
	v_mfma_f32_16x16x32_bf16 v[6:9], v[70:73], v[236:239], v[6:9]
	v_mfma_f32_16x16x32_bf16 v[46:49], v[74:77], v[200:203], 0
	v_mfma_f32_16x16x32_bf16 v[34:37], v[154:157], v[200:203], 0
	v_mfma_f32_16x16x32_bf16 v[26:29], v[74:77], v[224:227], 0
	v_mfma_f32_16x16x32_bf16 v[18:21], v[154:157], v[224:227], 0
	v_mfma_f32_16x16x32_bf16 v[14:17], v[74:77], v[232:235], 0
	v_mfma_f32_16x16x32_bf16 v[2:5], v[154:157], v[232:235], 0
	v_mfma_f32_16x16x32_bf16 v[50:53], v[74:77], v[192:195], 0
	v_mfma_f32_16x16x32_bf16 v[54:57], v[154:157], v[192:195], 0
	v_mfma_f32_16x16x32_bf16 v[46:49], v[86:89], v[204:207], v[46:49]
	v_mfma_f32_16x16x32_bf16 v[34:37], v[188:191], v[204:207], v[34:37]
	v_mfma_f32_16x16x32_bf16 v[26:29], v[86:89], v[228:231], v[26:29]
	v_mfma_f32_16x16x32_bf16 v[18:21], v[188:191], v[228:231], v[18:21]
	v_mfma_f32_16x16x32_bf16 v[14:17], v[86:89], v[236:239], v[14:17]
	v_mfma_f32_16x16x32_bf16 v[2:5], v[188:191], v[236:239], v[2:5]
	v_mfma_f32_16x16x32_bf16 v[50:53], v[86:89], v[196:199], v[50:53]
	v_mfma_f32_16x16x32_bf16 v[54:57], v[188:191], v[196:199], v[54:57]
	s_barrier
	s_setprio 0
	s_add_i32 s68, 0, 0x18000
	s_add_i32 s69, 0, 0x1c000
	v_add_u32_e32 v78, s68, v220
	v_add_u32_e32 v82, s69, v220
	ds_read_b128 v[66:69], v78
	ds_read_b128 v[70:73], v78 offset:1024
	ds_read_b128 v[74:77], v78 offset:2048
	ds_read_b128 v[78:81], v78 offset:3072
	ds_read_b128 v[86:89], v82
	ds_read_b128 v[154:157], v82 offset:1024
	ds_read_b128 v[188:191], v82 offset:2048
	ds_read_b128 v[192:195], v82 offset:3072
	s_add_u32 s24, s24, 0x100000
	s_addc_u32 s25, s25, 0
	s_mov_b32 m0, s12
	v_lshl_add_u64 v[240:241], s[24:25], 0, v[176:177]
	ds_read_b128 v[82:85], v222 offset:32768
	ds_read_b128 v[196:199], v222 offset:33792
	ds_read_b128 v[200:203], v222 offset:34816
	ds_read_b128 v[204:207], v222 offset:35840
	ds_read_b128 v[224:227], v222 offset:36864
	ds_read_b128 v[228:231], v222 offset:37888
	ds_read_b128 v[232:235], v222 offset:38912
	ds_read_b128 v[236:239], v222 offset:39936
	global_load_lds_dwordx4 v[240:241], off
	v_lshl_add_u64 v[240:241], s[24:25], 0, v[174:175]
	s_mov_b32 m0, s13
	s_nop 0
	global_load_lds_dwordx4 v[240:241], off
	s_waitcnt vmcnt(8)
	s_waitcnt lgkmcnt(0)
	s_setprio 1
	s_barrier
	v_mfma_f32_16x16x32_bf16 v[142:145], v[66:69], v[82:85], v[142:145]
	v_mfma_f32_16x16x32_bf16 v[130:133], v[74:77], v[82:85], v[130:133]
	v_mfma_f32_16x16x32_bf16 v[138:141], v[66:69], v[200:203], v[138:141]
	v_mfma_f32_16x16x32_bf16 v[126:129], v[74:77], v[200:203], v[126:129]
	v_mfma_f32_16x16x32_bf16 v[118:121], v[66:69], v[224:227], v[118:121]
	v_mfma_f32_16x16x32_bf16 v[110:113], v[74:77], v[224:227], v[110:113]
	v_mfma_f32_16x16x32_bf16 v[98:101], v[66:69], v[232:235], v[98:101]
	v_mfma_f32_16x16x32_bf16 v[94:97], v[74:77], v[232:235], v[94:97]
	v_mfma_f32_16x16x32_bf16 v[142:145], v[70:73], v[196:199], v[142:145]
	v_mfma_f32_16x16x32_bf16 v[130:133], v[78:81], v[196:199], v[130:133]
	v_mfma_f32_16x16x32_bf16 v[138:141], v[70:73], v[204:207], v[138:141]
	v_mfma_f32_16x16x32_bf16 v[126:129], v[78:81], v[204:207], v[126:129]
	v_mfma_f32_16x16x32_bf16 v[118:121], v[70:73], v[228:231], v[118:121]
	v_mfma_f32_16x16x32_bf16 v[110:113], v[78:81], v[228:231], v[110:113]
	v_mfma_f32_16x16x32_bf16 v[98:101], v[70:73], v[236:239], v[98:101]
	v_mfma_f32_16x16x32_bf16 v[94:97], v[78:81], v[236:239], v[94:97]
	v_mfma_f32_16x16x32_bf16 v[150:153], v[86:89], v[82:85], v[150:153]
	v_mfma_f32_16x16x32_bf16 v[82:85], v[188:191], v[82:85], v[146:149]
	v_mfma_f32_16x16x32_bf16 v[146:149], v[192:195], v[196:199], v[82:85]
	v_mfma_f32_16x16x32_bf16 v[82:85], v[86:89], v[200:203], v[134:137]
	v_mfma_f32_16x16x32_bf16 v[134:137], v[154:157], v[204:207], v[82:85]
	v_mfma_f32_16x16x32_bf16 v[82:85], v[188:191], v[200:203], v[122:125]
	v_mfma_f32_16x16x32_bf16 v[122:125], v[192:195], v[204:207], v[82:85]
	v_mfma_f32_16x16x32_bf16 v[82:85], v[86:89], v[224:227], v[114:117]
	v_mfma_f32_16x16x32_bf16 v[114:117], v[154:157], v[228:231], v[82:85]
	v_mfma_f32_16x16x32_bf16 v[82:85], v[188:191], v[224:227], v[106:109]
	v_mfma_f32_16x16x32_bf16 v[106:109], v[192:195], v[228:231], v[82:85]
	v_mfma_f32_16x16x32_bf16 v[82:85], v[86:89], v[232:235], v[102:105]
	v_mfma_f32_16x16x32_bf16 v[102:105], v[154:157], v[236:239], v[82:85]
	v_mfma_f32_16x16x32_bf16 v[82:85], v[188:191], v[232:235], v[90:93]
	v_mfma_f32_16x16x32_bf16 v[150:153], v[154:157], v[196:199], v[150:153]
	v_mfma_f32_16x16x32_bf16 v[90:93], v[192:195], v[236:239], v[82:85]
	s_barrier
; #define PG8_STAGE(bufoff, gbase, voff) do { _Pragma("unroll") for (int _i = 0; _i < 2; ++_i) \
;         __builtin_amdgcn_global_load_lds((const unsigned*)((const char*)(gbase) + (voff)[_i]), (PG8_LAS unsigned*)(lds + (bufoff) + ldsw + _i * 8192), 16, 0, 0); } while (0)
; #define PG8_LDA(dst, b, h) do { _Pragma("unroll") for (int m = 0; m < 4; ++m) _Pragma("unroll") for (int k = 0; k < 2; ++k) dst[m][k] = *(const PG8_LAS bf16x8*)(lds + PG8_SA(b, h) + aoff + m * 2048 + k * 1024); } while (0)
; #define PG8_LDB(dst, b, h) do { _Pragma("unroll") for (int n = 0; n < 2; ++n) _Pragma("unroll") for (int k = 0; k < 2; ++k) dst[n][k] = *(const PG8_LAS bf16x8*)(lds + PG8_SB(b, h) + boff + n * 2048 + k * 1024); } while (0)
; template <class Epi, class Sched, bool ALIGN_EPI = false, bool SP2 = false>
; __device__ __forceinline__ void gemm_phase(PG8_LAS unsigned char* lds, const Gemm g, const Sched& S, const Epi& E) {
;     ...
;         for (int t = 0; t < nt; t += 2) {
;             const bool last = (t == nt - 2);
;             const char* a1 = cA + (size_t)(t + 1) * kstep;
;             const char* a2 = last ? nA : cA + (size_t)(t + 2) * kstep; const char* b2 = last ? nB : cB + (size_t)(t + 2) * kstep;
;             const char* a3 = a2 + kstep; const char* b3 = b2 + kstep;
;             if (last && has_next) S.a_ready(nxt);
;             if constexpr (SP2) {
;             PG8_LDB(B0, 0, 0); PG8_LDB(B1, 0, 1); PG8_SCHED; PG8_LDA(At, 0, 0); PG8_STAGE(PG8_SA(1, 1), a1 + hstep, voffA);
;             PG8_WAIT_V(8); PG8_WAIT_L(0); PG8_BAR; PG8_MMA(0, 0, At, B0); PG8_MMA(0, 1, At, B1); PG8_BAR; PG8_SCHED;
;             PG8_LDA(At, 0, 1); PG8_STAGE(PG8_SB(0, 0), b2, voffB); PG8_STAGE(PG8_SB(0, 1), b2 + hstep, voffB); PG8_STAGE(PG8_SA(0, 0), a2, voffA);
;             PG8_WAIT_V(8); PG8_WAIT_L(0); PG8_BAR; PG8_MMA(1, 0, At, B0); PG8_MMA(1, 1, At, B1); PG8_BAR; PG8_SCHED;
;             PG8_LDB(B0, 1, 0); PG8_LDB(B1, 1, 1); PG8_SCHED; PG8_LDA(At, 1, 0); PG8_STAGE(PG8_SA(0, 1), a2 + hstep, voffA);
;             PG8_WAIT_V(8); PG8_WAIT_L(0); PG8_BAR; PG8_MMA(0, 0, At, B0); PG8_MMA(0, 1, At, B1); PG8_BAR; PG8_SCHED;
;             PG8_LDA(At, 1, 1); PG8_STAGE(PG8_SB(1, 0), b3, voffB); PG8_STAGE(PG8_SB(1, 1), b3 + hstep, voffB); PG8_STAGE(PG8_SA(1, 0), a3, voffA);
;             PG8_WAIT_V(8); PG8_WAIT_L(0); PG8_BAR; PG8_MMA(1, 0, At, B0); PG8_MMA(1, 1, At, B1); PG8_BAR; PG8_SCHED;
	s_setprio 0
	s_add_i32 s24, s68, s9
	s_nop 2
	v_lshl_add_u64 v[82:83], v[170:171], 0, s[96:97]
	s_mov_b32 m0, s24
	ds_read_b128 v[196:199], v222 offset:49152
	ds_read_b128 v[200:203], v222 offset:50176
	ds_read_b128 v[204:207], v222 offset:51200
	ds_read_b128 v[224:227], v222 offset:52224
	ds_read_b128 v[228:231], v222 offset:53248
	ds_read_b128 v[232:235], v222 offset:54272
	ds_read_b128 v[236:239], v222 offset:55296
	ds_read_b128 v[240:243], v222 offset:56320
	global_load_lds_dwordx4 v[82:83], off
	s_add_i32 m0, s24, 0x2000
	s_add_u32 s22, s22, 0x100080
	v_lshl_add_u64 v[82:83], v[208:209], 0, s[96:97]
	s_addc_u32 s23, s23, 0
	s_add_i32 s24, s69, s9
	global_load_lds_dwordx4 v[82:83], off
	v_lshl_add_u64 v[82:83], s[22:23], 0, v[158:159]
	s_mov_b32 m0, s24
	s_nop 0
	global_load_lds_dwordx4 v[82:83], off
	v_lshl_add_u64 v[82:83], s[22:23], 0, v[172:173]
	s_add_i32 m0, s24, 0x2000
	s_nop 0
	global_load_lds_dwordx4 v[82:83], off
	v_lshl_add_u64 v[82:83], v[210:211], 0, s[96:97]
	s_mov_b32 m0, s0
	s_nop 0
	global_load_lds_dwordx4 v[82:83], off
	v_lshl_add_u64 v[82:83], v[244:245], 0, s[96:97]
	s_mov_b32 m0, s34
	s_nop 0
	global_load_lds_dwordx4 v[82:83], off
	s_waitcnt vmcnt(8)
	s_waitcnt lgkmcnt(0)
	s_setprio 1
	s_barrier
	v_mfma_f32_16x16x32_bf16 v[62:65], v[66:69], v[196:199], v[62:65]
	v_mfma_f32_16x16x32_bf16 v[42:45], v[74:77], v[196:199], v[42:45]
	v_mfma_f32_16x16x32_bf16 v[58:61], v[66:69], v[204:207], v[58:61]
	v_mfma_f32_16x16x32_bf16 v[38:41], v[74:77], v[204:207], v[38:41]
	v_mfma_f32_16x16x32_bf16 v[30:33], v[66:69], v[228:231], v[30:33]
	v_mfma_f32_16x16x32_bf16 v[22:25], v[74:77], v[228:231], v[22:25]
	v_mfma_f32_16x16x32_bf16 v[10:13], v[66:69], v[236:239], v[10:13]
	v_mfma_f32_16x16x32_bf16 v[6:9], v[74:77], v[236:239], v[6:9]
	v_mfma_f32_16x16x32_bf16 v[62:65], v[70:73], v[200:203], v[62:65]
	v_mfma_f32_16x16x32_bf16 v[42:45], v[78:81], v[200:203], v[42:45]
	v_mfma_f32_16x16x32_bf16 v[58:61], v[70:73], v[224:227], v[58:61]
	v_mfma_f32_16x16x32_bf16 v[38:41], v[78:81], v[224:227], v[38:41]
	v_mfma_f32_16x16x32_bf16 v[30:33], v[70:73], v[232:235], v[30:33]
	v_mfma_f32_16x16x32_bf16 v[22:25], v[78:81], v[232:235], v[22:25]
	v_mfma_f32_16x16x32_bf16 v[10:13], v[70:73], v[240:243], v[10:13]
	v_mfma_f32_16x16x32_bf16 v[6:9], v[78:81], v[240:243], v[6:9]
	v_mfma_f32_16x16x32_bf16 v[50:53], v[86:89], v[196:199], v[50:53]
	v_mfma_f32_16x16x32_bf16 v[82:85], v[154:157], v[200:203], v[50:53]
	v_mfma_f32_16x16x32_bf16 v[50:53], v[188:191], v[196:199], v[54:57]
	v_mfma_f32_16x16x32_bf16 v[46:49], v[86:89], v[204:207], v[46:49]
	v_mfma_f32_16x16x32_bf16 v[34:37], v[188:191], v[204:207], v[34:37]
	v_mfma_f32_16x16x32_bf16 v[26:29], v[86:89], v[228:231], v[26:29]
	v_mfma_f32_16x16x32_bf16 v[18:21], v[188:191], v[228:231], v[18:21]
	v_mfma_f32_16x16x32_bf16 v[14:17], v[86:89], v[236:239], v[14:17]
	v_mfma_f32_16x16x32_bf16 v[2:5], v[188:191], v[236:239], v[2:5]
	v_mfma_f32_16x16x32_bf16 v[78:81], v[192:195], v[200:203], v[50:53]
	v_mfma_f32_16x16x32_bf16 v[46:49], v[154:157], v[224:227], v[46:49]
	v_mfma_f32_16x16x32_bf16 v[34:37], v[192:195], v[224:227], v[34:37]
	v_mfma_f32_16x16x32_bf16 v[26:29], v[154:157], v[232:235], v[26:29]
	v_mfma_f32_16x16x32_bf16 v[18:21], v[192:195], v[232:235], v[18:21]
	v_mfma_f32_16x16x32_bf16 v[14:17], v[154:157], v[240:243], v[14:17]
	v_mfma_f32_16x16x32_bf16 v[2:5], v[192:195], v[240:243], v[2:5]
	s_barrier
	s_setprio 0
	s_add_i32 s65, s65, 2
	s_add_u32 s16, s16, 0x100
	s_addc_u32 s17, s17, 0
	s_add_u32 vcc_lo, vcc_lo, 0x100
	s_addc_u32 vcc_hi, vcc_hi, 0
	s_cmp_gt_u32 s65, 61
	s_cbranch_scc1 .Lpeel_exit_3

; #define PG8_BAR __builtin_amdgcn_s_barrier()
; template <class Epi, class Sched, bool ALIGN_EPI = false, bool SP2 = false>
; __device__ __forceinline__ void gemm_phase(PG8_LAS unsigned char* lds, const Gemm g, const Sched& S, const Epi& E) {
;     ...
;         if constexpr (ALIGN_EPI) { if (wr == 0) PG8_BAR; }
;         if constexpr (!Epi::AFTER_DRAIN) { E(acc, cur, wr, wc, fr, fq); S.done(cur); }
.Lpeel_exit_3:
	s_and_b64 vcc, exec, s[54:55]
	s_cbranch_vccz .LBB0_713
	s_barrier

;     __host__ __device__ bool next(int i, Unit& u) const { return at((long)i * G + c, u); }
; #define PG8_STAGE(bufoff, gbase, voff) do { _Pragma("unroll") for (int _i = 0; _i < 2; ++_i) \
;         __builtin_amdgcn_global_load_lds((const unsigned*)((const char*)(gbase) + (voff)[_i]), (PG8_LAS unsigned*)(lds + (bufoff) + ldsw + _i * 8192), 16, 0, 0); } while (0)
; #define PG8_LDA(dst, b, h) do { _Pragma("unroll") for (int m = 0; m < 4; ++m) _Pragma("unroll") for (int k = 0; k < 2; ++k) dst[m][k] = *(const PG8_LAS bf16x8*)(lds + PG8_SA(b, h) + aoff + m * 2048 + k * 1024); } while (0)
; #define PG8_LDB(dst, b, h) do { _Pragma("unroll") for (int n = 0; n < 2; ++n) _Pragma("unroll") for (int k = 0; k < 2; ++k) dst[n][k] = *(const PG8_LAS bf16x8*)(lds + PG8_SB(b, h) + boff + n * 2048 + k * 1024); } while (0)
; #define PG8_WAIT_V(n) asm volatile("s_waitcnt vmcnt(" #n ")" ::: "memory")
; #define PG8_BAR __builtin_amdgcn_s_barrier()
; template <class Epi, class Sched, bool ALIGN_EPI = false, bool SP2 = false>
; __device__ __forceinline__ void gemm_phase(PG8_LAS unsigned char* lds, const Gemm g, const Sched& S, const Epi& E) {
;     ...
;         const bool has_next = S.next(ui + 1, nxt);
;         const char* nA = has_next ? (const char*)g.A + (size_t)nxt.pm * tstep + (size_t)nxt.k0 * kstep : cA; const char* nB = has_next ? (const char*)g.Bt + (size_t)nxt.pn * tstep + (size_t)nxt.k0 * kstep : cB;
;         const int nt = cur.nt;
;         for (int t = 0; t < nt; t += 2) {
;             const bool last = (t == nt - 2);
;             const char* a1 = cA + (size_t)(t + 1) * kstep;
;             const char* a2 = last ? nA : cA + (size_t)(t + 2) * kstep; const char* b2 = last ? nB : cB + (size_t)(t + 2) * kstep;
;             const char* a3 = a2 + kstep; const char* b3 = b2 + kstep;
;             if (last && has_next) S.a_ready(nxt);
;             if constexpr (SP2) {
;             PG8_LDB(B0, 0, 0); PG8_LDB(B1, 0, 1); PG8_SCHED; PG8_LDA(At, 0, 0); PG8_STAGE(PG8_SA(1, 1), a1 + hstep, voffA);
;             PG8_WAIT_V(8); PG8_WAIT_L(0); PG8_BAR; PG8_MMA(0, 0, At, B0); PG8_MMA(0, 1, At, B1); PG8_BAR; PG8_SCHED;
;             PG8_LDA(At, 0, 1); PG8_STAGE(PG8_SB(0, 0), b2, voffB); PG8_STAGE(PG8_SB(0, 1), b2 + hstep, voffB); PG8_STAGE(PG8_SA(0, 0), a2, voffA);
;             PG8_WAIT_V(8); PG8_WAIT_L(0); PG8_BAR; PG8_MMA(1, 0, At, B0); PG8_MMA(1, 1, At, B1); PG8_BAR; PG8_SCHED;
.LBB0_914:
	s_add_i32 s15, s14, -2
	s_add_u32 s16, s50, 0x100
	s_addc_u32 s17, s51, 0
	s_mov_b32 s28, 0
	s_waitcnt vmcnt(0)
	s_waitcnt vmcnt(0)
	s_add_i32 s30, s28, 2
	s_add_u32 s26, s48, 0x100
	s_addc_u32 s27, s49, 0
	s_add_i32 s43, 0, 0x10000
	s_cmp_eq_u32 s15, s28
	s_cselect_b32 s51, s45, s27
	s_cselect_b32 s50, s44, s26
	s_cselect_b32 s29, s47, s17
	s_cselect_b32 s28, s46, s16
	s_add_i32 s59, 0, 0x14000
	v_add_u32_e32 v142, s43, v188
	v_add_u32_e32 v170, s59, v188
	ds_read_b128 v[130:133], v142
	ds_read_b128 v[134:137], v142 offset:1024
	ds_read_b128 v[138:141], v142 offset:2048
	ds_read_b128 v[142:145], v142 offset:3072
	ds_read_b128 v[146:149], v170
	ds_read_b128 v[150:153], v170 offset:1024
	ds_read_b128 v[178:181], v170 offset:2048
	ds_read_b128 v[182:185], v170 offset:3072
	v_lshl_add_u64 v[170:171], s[48:49], 0, v[176:177]
	s_add_i32 m0, s9, 0xc000
	ds_read_b128 v[192:195], v190
	ds_read_b128 v[196:199], v190 offset:1024
	ds_read_b128 v[200:203], v190 offset:2048
	ds_read_b128 v[204:207], v190 offset:3072
	ds_read_b128 v[220:223], v190 offset:4096
	ds_read_b128 v[224:227], v190 offset:5120
	ds_read_b128 v[228:231], v190 offset:6144
	ds_read_b128 v[232:235], v190 offset:7168
	global_load_lds_dwordx4 v[170:171], off
	v_lshl_add_u64 v[170:171], s[48:49], 0, v[174:175]
	s_add_i32 m0, s9, 0xe000
	s_nop 0
	global_load_lds_dwordx4 v[170:171], off
	s_waitcnt vmcnt(8)
	s_waitcnt lgkmcnt(0)
	s_setprio 1
	s_barrier
	v_mfma_f32_16x16x32_bf16 v[126:129], v[130:133], v[192:195], 0
	v_mfma_f32_16x16x32_bf16 v[122:125], v[138:141], v[192:195], 0
	v_mfma_f32_16x16x32_bf16 v[118:121], v[130:133], v[200:203], 0
	v_mfma_f32_16x16x32_bf16 v[114:117], v[138:141], v[200:203], 0
	v_mfma_f32_16x16x32_bf16 v[102:105], v[130:133], v[220:223], 0
	v_mfma_f32_16x16x32_bf16 v[94:97], v[138:141], v[220:223], 0
	v_mfma_f32_16x16x32_bf16 v[86:89], v[130:133], v[228:231], 0
	v_mfma_f32_16x16x32_bf16 v[78:81], v[138:141], v[228:231], 0
	v_mfma_f32_16x16x32_bf16 v[126:129], v[134:137], v[196:199], v[126:129]
	v_mfma_f32_16x16x32_bf16 v[122:125], v[142:145], v[196:199], v[122:125]
	v_mfma_f32_16x16x32_bf16 v[118:121], v[134:137], v[204:207], v[118:121]
	v_mfma_f32_16x16x32_bf16 v[114:117], v[142:145], v[204:207], v[114:117]
	v_mfma_f32_16x16x32_bf16 v[102:105], v[134:137], v[224:227], v[102:105]
	v_mfma_f32_16x16x32_bf16 v[94:97], v[142:145], v[224:227], v[94:97]
	v_mfma_f32_16x16x32_bf16 v[86:89], v[134:137], v[232:235], v[86:89]
	v_mfma_f32_16x16x32_bf16 v[78:81], v[142:145], v[232:235], v[78:81]
	v_mfma_f32_16x16x32_bf16 v[110:113], v[146:149], v[192:195], 0
	v_mfma_f32_16x16x32_bf16 v[106:109], v[178:181], v[192:195], 0
	v_mfma_f32_16x16x32_bf16 v[98:101], v[146:149], v[200:203], 0
	v_mfma_f32_16x16x32_bf16 v[90:93], v[178:181], v[200:203], 0
	v_mfma_f32_16x16x32_bf16 v[82:85], v[146:149], v[220:223], 0
	v_mfma_f32_16x16x32_bf16 v[74:77], v[178:181], v[220:223], 0
	v_mfma_f32_16x16x32_bf16 v[70:73], v[146:149], v[228:231], 0
	v_mfma_f32_16x16x32_bf16 v[66:69], v[178:181], v[228:231], 0
	v_mfma_f32_16x16x32_bf16 v[110:113], v[150:153], v[196:199], v[110:113]
	v_mfma_f32_16x16x32_bf16 v[106:109], v[182:185], v[196:199], v[106:109]
	v_mfma_f32_16x16x32_bf16 v[98:101], v[150:153], v[204:207], v[98:101]
	v_mfma_f32_16x16x32_bf16 v[90:93], v[182:185], v[204:207], v[90:93]
	v_mfma_f32_16x16x32_bf16 v[82:85], v[150:153], v[224:227], v[82:85]
	v_mfma_f32_16x16x32_bf16 v[74:77], v[182:185], v[224:227], v[74:77]
	v_mfma_f32_16x16x32_bf16 v[70:73], v[150:153], v[232:235], v[70:73]
	v_mfma_f32_16x16x32_bf16 v[66:69], v[182:185], v[232:235], v[66:69]
	s_barrier
	s_setprio 0
	s_add_i32 s43, s43, s8
	v_lshl_add_u64 v[170:171], s[28:29], 0, v[158:159]
	s_mov_b32 m0, s43
	ds_read_b128 v[192:195], v190 offset:16384
	ds_read_b128 v[196:199], v190 offset:17408
	ds_read_b128 v[200:203], v190 offset:18432
	ds_read_b128 v[204:207], v190 offset:19456
	ds_read_b128 v[220:223], v190 offset:20480
	ds_read_b128 v[224:227], v190 offset:21504
	ds_read_b128 v[228:231], v190 offset:22528
	ds_read_b128 v[232:235], v190 offset:23552
	global_load_lds_dwordx4 v[170:171], off
	s_add_i32 m0, s43, 0x2000
	s_add_u32 s48, s28, 0x2b0000
	v_lshl_add_u64 v[186:187], s[28:29], 0, v[172:173]
	s_addc_u32 s49, s29, 0
	s_add_i32 s43, s59, s8
	global_load_lds_dwordx4 v[186:187], off
	v_lshl_add_u64 v[208:209], s[48:49], 0, v[158:159]
	s_mov_b32 m0, s43
	v_lshl_add_u64 v[210:211], s[50:51], 0, v[156:157]
	global_load_lds_dwordx4 v[208:209], off
	v_lshl_add_u64 v[208:209], s[48:49], 0, v[172:173]
	s_add_i32 m0, s43, 0x2000
	s_nop 0
	global_load_lds_dwordx4 v[208:209], off
	v_lshl_add_u64 v[208:209], s[50:51], 0, v[154:155]
	s_mov_b32 m0, s9
	s_nop 0
	global_load_lds_dwordx4 v[208:209], off
	s_mov_b32 m0, s10
	s_nop 0
	global_load_lds_dwordx4 v[210:211], off
	s_waitcnt vmcnt(8)
	s_waitcnt lgkmcnt(0)
	s_setprio 1
	s_barrier
; #define PG8_STAGE(bufoff, gbase, voff) do { _Pragma("unroll") for (int _i = 0; _i < 2; ++_i) \
;         __builtin_amdgcn_global_load_lds((const unsigned*)((const char*)(gbase) + (voff)[_i]), (PG8_LAS unsigned*)(lds + (bufoff) + ldsw + _i * 8192), 16, 0, 0); } while (0)
; #define PG8_LDA(dst, b, h) do { _Pragma("unroll") for (int m = 0; m < 4; ++m) _Pragma("unroll") for (int k = 0; k < 2; ++k) dst[m][k] = *(const PG8_LAS bf16x8*)(lds + PG8_SA(b, h) + aoff + m * 2048 + k * 1024); } while (0)
; #define PG8_LDB(dst, b, h) do { _Pragma("unroll") for (int n = 0; n < 2; ++n) _Pragma("unroll") for (int k = 0; k < 2; ++k) dst[n][k] = *(const PG8_LAS bf16x8*)(lds + PG8_SB(b, h) + boff + n * 2048 + k * 1024); } while (0)
; #define PG8_MMA(ai, bj, At, Bt) do { __builtin_amdgcn_s_setprio(1); _Pragma("unroll") for (int m = 0; m < 4; ++m) _Pragma("unroll") for (int n = 0; n < 2; ++n) _Pragma("unroll") for (int k = 0; k < 2; ++k) \
;         acc[ai][bj][m][n] = __builtin_amdgcn_mfma_f32_16x16x32_bf16(Bt[n][k], At[m][k], acc[ai][bj][m][n], 0, 0, 0); __builtin_amdgcn_s_setprio(0); } while (0)
; #define PG8_WAIT_V(n) asm volatile("s_waitcnt vmcnt(" #n ")" ::: "memory")
; #define PG8_WAIT_L(n) asm volatile("s_waitcnt lgkmcnt(" #n ")" ::: "memory")
; #define PG8_BAR __builtin_amdgcn_s_barrier()
; #define PG8_SCHED __builtin_amdgcn_sched_barrier(0)
; template <class Epi, class Sched, bool ALIGN_EPI = false, bool SP2 = false>
; __device__ __forceinline__ void gemm_phase(PG8_LAS unsigned char* lds, const Gemm g, const Sched& S, const Epi& E) {
;     ...
;             PG8_WAIT_V(8); PG8_WAIT_L(0); PG8_BAR; PG8_MMA(1, 0, At, B0); PG8_MMA(1, 1, At, B1); PG8_BAR; PG8_SCHED;
;             PG8_LDB(B0, 1, 0); PG8_LDB(B1, 1, 1); PG8_SCHED; PG8_LDA(At, 1, 0); PG8_STAGE(PG8_SA(0, 1), a2 + hstep, voffA);
;             PG8_WAIT_V(8); PG8_WAIT_L(0); PG8_BAR; PG8_MMA(0, 0, At, B0); PG8_MMA(0, 1, At, B1); PG8_BAR; PG8_SCHED;
	v_mfma_f32_16x16x32_bf16 v[62:65], v[130:133], v[192:195], 0
	v_mfma_f32_16x16x32_bf16 v[58:61], v[138:141], v[192:195], 0
	v_mfma_f32_16x16x32_bf16 v[54:57], v[130:133], v[200:203], 0
	v_mfma_f32_16x16x32_bf16 v[46:49], v[138:141], v[200:203], 0
	v_mfma_f32_16x16x32_bf16 v[38:41], v[130:133], v[220:223], 0
	v_mfma_f32_16x16x32_bf16 v[30:33], v[138:141], v[220:223], 0
	v_mfma_f32_16x16x32_bf16 v[22:25], v[130:133], v[228:231], 0
	v_mfma_f32_16x16x32_bf16 v[14:17], v[138:141], v[228:231], 0
	v_mfma_f32_16x16x32_bf16 v[62:65], v[134:137], v[196:199], v[62:65]
	v_mfma_f32_16x16x32_bf16 v[58:61], v[142:145], v[196:199], v[58:61]
	v_mfma_f32_16x16x32_bf16 v[54:57], v[134:137], v[204:207], v[54:57]
	v_mfma_f32_16x16x32_bf16 v[46:49], v[142:145], v[204:207], v[46:49]
	v_mfma_f32_16x16x32_bf16 v[38:41], v[134:137], v[224:227], v[38:41]
	v_mfma_f32_16x16x32_bf16 v[30:33], v[142:145], v[224:227], v[30:33]
	v_mfma_f32_16x16x32_bf16 v[22:25], v[134:137], v[232:235], v[22:25]
	v_mfma_f32_16x16x32_bf16 v[14:17], v[142:145], v[232:235], v[14:17]
	v_mfma_f32_16x16x32_bf16 v[50:53], v[146:149], v[192:195], 0
	v_mfma_f32_16x16x32_bf16 v[42:45], v[178:181], v[192:195], 0
	v_mfma_f32_16x16x32_bf16 v[34:37], v[146:149], v[200:203], 0
	v_mfma_f32_16x16x32_bf16 v[26:29], v[178:181], v[200:203], 0
	v_mfma_f32_16x16x32_bf16 v[18:21], v[146:149], v[220:223], 0
	v_mfma_f32_16x16x32_bf16 v[10:13], v[178:181], v[220:223], 0
	v_mfma_f32_16x16x32_bf16 v[6:9], v[146:149], v[228:231], 0
	v_mfma_f32_16x16x32_bf16 v[2:5], v[178:181], v[228:231], 0
	v_mfma_f32_16x16x32_bf16 v[50:53], v[150:153], v[196:199], v[50:53]
	v_mfma_f32_16x16x32_bf16 v[42:45], v[182:185], v[196:199], v[42:45]
	v_mfma_f32_16x16x32_bf16 v[34:37], v[150:153], v[204:207], v[34:37]
	v_mfma_f32_16x16x32_bf16 v[26:29], v[182:185], v[204:207], v[26:29]
	v_mfma_f32_16x16x32_bf16 v[18:21], v[150:153], v[224:227], v[18:21]
	v_mfma_f32_16x16x32_bf16 v[10:13], v[182:185], v[224:227], v[10:13]
	v_mfma_f32_16x16x32_bf16 v[6:9], v[150:153], v[232:235], v[6:9]
	v_mfma_f32_16x16x32_bf16 v[2:5], v[182:185], v[232:235], v[2:5]
	s_barrier
	s_setprio 0
	s_add_i32 s43, 0, 0x18000
	s_add_i32 s59, 0, 0x1c000
	v_add_u32_e32 v142, s43, v188
	v_add_u32_e32 v182, s59, v188
	ds_read_b128 v[130:133], v142
	ds_read_b128 v[134:137], v142 offset:1024
	ds_read_b128 v[138:141], v142 offset:2048
	ds_read_b128 v[142:145], v142 offset:3072
	ds_read_b128 v[146:149], v182
	ds_read_b128 v[150:153], v182 offset:1024
	ds_read_b128 v[178:181], v182 offset:2048
	ds_read_b128 v[182:185], v182 offset:3072
	s_add_u32 s48, s50, 0x2b0000
	s_addc_u32 s49, s51, 0
	s_mov_b32 m0, s11
	v_lshl_add_u64 v[236:237], s[48:49], 0, v[154:155]
	ds_read_b128 v[192:195], v190 offset:32768
	ds_read_b128 v[196:199], v190 offset:33792
	ds_read_b128 v[200:203], v190 offset:34816
	ds_read_b128 v[204:207], v190 offset:35840
	ds_read_b128 v[220:223], v190 offset:36864
	ds_read_b128 v[224:227], v190 offset:37888
	ds_read_b128 v[228:231], v190 offset:38912
	ds_read_b128 v[232:235], v190 offset:39936
	global_load_lds_dwordx4 v[236:237], off
	v_lshl_add_u64 v[236:237], s[48:49], 0, v[156:157]
	s_mov_b32 m0, s12
	s_nop 0
	global_load_lds_dwordx4 v[236:237], off
	s_waitcnt vmcnt(8)
	s_waitcnt lgkmcnt(0)
	s_setprio 1
	s_barrier
	v_mfma_f32_16x16x32_bf16 v[126:129], v[130:133], v[192:195], v[126:129]
	v_mfma_f32_16x16x32_bf16 v[122:125], v[138:141], v[192:195], v[122:125]
	v_mfma_f32_16x16x32_bf16 v[118:121], v[130:133], v[200:203], v[118:121]
	v_mfma_f32_16x16x32_bf16 v[114:117], v[138:141], v[200:203], v[114:117]
	v_mfma_f32_16x16x32_bf16 v[102:105], v[130:133], v[220:223], v[102:105]
	v_mfma_f32_16x16x32_bf16 v[94:97], v[138:141], v[220:223], v[94:97]
	v_mfma_f32_16x16x32_bf16 v[86:89], v[130:133], v[228:231], v[86:89]
	v_mfma_f32_16x16x32_bf16 v[78:81], v[138:141], v[228:231], v[78:81]
	v_mfma_f32_16x16x32_bf16 v[126:129], v[134:137], v[196:199], v[126:129]
	v_mfma_f32_16x16x32_bf16 v[122:125], v[142:145], v[196:199], v[122:125]
	v_mfma_f32_16x16x32_bf16 v[118:121], v[134:137], v[204:207], v[118:121]
	v_mfma_f32_16x16x32_bf16 v[114:117], v[142:145], v[204:207], v[114:117]
	v_mfma_f32_16x16x32_bf16 v[102:105], v[134:137], v[224:227], v[102:105]
	v_mfma_f32_16x16x32_bf16 v[94:97], v[142:145], v[224:227], v[94:97]
	v_mfma_f32_16x16x32_bf16 v[86:89], v[134:137], v[232:235], v[86:89]
	v_mfma_f32_16x16x32_bf16 v[78:81], v[142:145], v[232:235], v[78:81]
	v_mfma_f32_16x16x32_bf16 v[110:113], v[146:149], v[192:195], v[110:113]
	v_mfma_f32_16x16x32_bf16 v[106:109], v[178:181], v[192:195], v[106:109]
	v_mfma_f32_16x16x32_bf16 v[98:101], v[146:149], v[200:203], v[98:101]
	v_mfma_f32_16x16x32_bf16 v[90:93], v[178:181], v[200:203], v[90:93]
	v_mfma_f32_16x16x32_bf16 v[82:85], v[146:149], v[220:223], v[82:85]
	v_mfma_f32_16x16x32_bf16 v[74:77], v[178:181], v[220:223], v[74:77]
	v_mfma_f32_16x16x32_bf16 v[70:73], v[146:149], v[228:231], v[70:73]
	v_mfma_f32_16x16x32_bf16 v[66:69], v[178:181], v[228:231], v[66:69]
	v_mfma_f32_16x16x32_bf16 v[110:113], v[150:153], v[196:199], v[110:113]
	v_mfma_f32_16x16x32_bf16 v[106:109], v[182:185], v[196:199], v[106:109]
	v_mfma_f32_16x16x32_bf16 v[98:101], v[150:153], v[204:207], v[98:101]
	v_mfma_f32_16x16x32_bf16 v[90:93], v[182:185], v[204:207], v[90:93]
	v_mfma_f32_16x16x32_bf16 v[82:85], v[150:153], v[224:227], v[82:85]
	v_mfma_f32_16x16x32_bf16 v[74:77], v[182:185], v[224:227], v[74:77]
	v_mfma_f32_16x16x32_bf16 v[70:73], v[150:153], v[232:235], v[70:73]
	v_mfma_f32_16x16x32_bf16 v[66:69], v[182:185], v[232:235], v[66:69]
	s_barrier
; #define PG8_STAGE(bufoff, gbase, voff) do { _Pragma("unroll") for (int _i = 0; _i < 2; ++_i) \
;         __builtin_amdgcn_global_load_lds((const unsigned*)((const char*)(gbase) + (voff)[_i]), (PG8_LAS unsigned*)(lds + (bufoff) + ldsw + _i * 8192), 16, 0, 0); } while (0)
; #define PG8_LDA(dst, b, h) do { _Pragma("unroll") for (int m = 0; m < 4; ++m) _Pragma("unroll") for (int k = 0; k < 2; ++k) dst[m][k] = *(const PG8_LAS bf16x8*)(lds + PG8_SA(b, h) + aoff + m * 2048 + k * 1024); } while (0)
; #define PG8_LDB(dst, b, h) do { _Pragma("unroll") for (int n = 0; n < 2; ++n) _Pragma("unroll") for (int k = 0; k < 2; ++k) dst[n][k] = *(const PG8_LAS bf16x8*)(lds + PG8_SB(b, h) + boff + n * 2048 + k * 1024); } while (0)
; template <class Epi, class Sched, bool ALIGN_EPI = false, bool SP2 = false>
; __device__ __forceinline__ void gemm_phase(PG8_LAS unsigned char* lds, const Gemm g, const Sched& S, const Epi& E) {
;     ...
;         for (int t = 0; t < nt; t += 2) {
;             const bool last = (t == nt - 2);
;             const char* a1 = cA + (size_t)(t + 1) * kstep;
;             const char* a2 = last ? nA : cA + (size_t)(t + 2) * kstep; const char* b2 = last ? nB : cB + (size_t)(t + 2) * kstep;
;             const char* a3 = a2 + kstep; const char* b3 = b2 + kstep;
;             if (last && has_next) S.a_ready(nxt);
;             if constexpr (SP2) {
;             PG8_LDB(B0, 0, 0); PG8_LDB(B1, 0, 1); PG8_SCHED; PG8_LDA(At, 0, 0); PG8_STAGE(PG8_SA(1, 1), a1 + hstep, voffA);
;             PG8_WAIT_V(8); PG8_WAIT_L(0); PG8_BAR; PG8_MMA(0, 0, At, B0); PG8_MMA(0, 1, At, B1); PG8_BAR; PG8_SCHED;
;             PG8_LDA(At, 0, 1); PG8_STAGE(PG8_SB(0, 0), b2, voffB); PG8_STAGE(PG8_SB(0, 1), b2 + hstep, voffB); PG8_STAGE(PG8_SA(0, 0), a2, voffA);
;             PG8_WAIT_V(8); PG8_WAIT_L(0); PG8_BAR; PG8_MMA(1, 0, At, B0); PG8_MMA(1, 1, At, B1); PG8_BAR; PG8_SCHED;
;             PG8_LDB(B0, 1, 0); PG8_LDB(B1, 1, 1); PG8_SCHED; PG8_LDA(At, 1, 0); PG8_STAGE(PG8_SA(0, 1), a2 + hstep, voffA);
;             PG8_WAIT_V(8); PG8_WAIT_L(0); PG8_BAR; PG8_MMA(0, 0, At, B0); PG8_MMA(0, 1, At, B1); PG8_BAR; PG8_SCHED;
;             PG8_LDA(At, 1, 1); PG8_STAGE(PG8_SB(1, 0), b3, voffB); PG8_STAGE(PG8_SB(1, 1), b3 + hstep, voffB); PG8_STAGE(PG8_SA(1, 0), a3, voffA);
;             PG8_WAIT_V(8); PG8_WAIT_L(0); PG8_BAR; PG8_MMA(1, 0, At, B0); PG8_MMA(1, 1, At, B1); PG8_BAR; PG8_SCHED;
	s_setprio 0
	s_add_i32 s43, s43, s8
	v_lshl_add_u64 v[170:171], v[170:171], 0, s[96:97]
	s_mov_b32 m0, s43
	ds_read_b128 v[192:195], v190 offset:49152
	ds_read_b128 v[196:199], v190 offset:50176
	ds_read_b128 v[200:203], v190 offset:51200
	ds_read_b128 v[204:207], v190 offset:52224
	ds_read_b128 v[220:223], v190 offset:53248
	ds_read_b128 v[224:227], v190 offset:54272
	ds_read_b128 v[228:231], v190 offset:55296
	ds_read_b128 v[232:235], v190 offset:56320
	global_load_lds_dwordx4 v[170:171], off
	s_add_i32 m0, s43, 0x2000
	s_add_u32 s28, s28, 0x2b0080
	v_lshl_add_u64 v[170:171], v[186:187], 0, s[96:97]
	s_addc_u32 s29, s29, 0
	s_add_i32 s43, s59, s8
	global_load_lds_dwordx4 v[170:171], off
	v_lshl_add_u64 v[170:171], s[28:29], 0, v[158:159]
	s_mov_b32 m0, s43
	s_nop 0
	global_load_lds_dwordx4 v[170:171], off
	v_lshl_add_u64 v[170:171], s[28:29], 0, v[172:173]
	s_add_i32 m0, s43, 0x2000
	s_nop 0
	global_load_lds_dwordx4 v[170:171], off
	v_lshl_add_u64 v[170:171], v[208:209], 0, s[96:97]
	s_mov_b32 m0, s35
	s_nop 0
	global_load_lds_dwordx4 v[170:171], off
	v_lshl_add_u64 v[170:171], v[210:211], 0, s[96:97]
	s_mov_b32 m0, s52
	s_nop 0
	global_load_lds_dwordx4 v[170:171], off
	s_waitcnt vmcnt(8)
	s_waitcnt lgkmcnt(0)
	s_setprio 1
	s_barrier
	v_mfma_f32_16x16x32_bf16 v[62:65], v[130:133], v[192:195], v[62:65]
	v_mfma_f32_16x16x32_bf16 v[58:61], v[138:141], v[192:195], v[58:61]
	v_mfma_f32_16x16x32_bf16 v[54:57], v[130:133], v[200:203], v[54:57]
	v_mfma_f32_16x16x32_bf16 v[46:49], v[138:141], v[200:203], v[46:49]
	v_mfma_f32_16x16x32_bf16 v[38:41], v[130:133], v[220:223], v[38:41]
	v_mfma_f32_16x16x32_bf16 v[30:33], v[138:141], v[220:223], v[30:33]
	v_mfma_f32_16x16x32_bf16 v[22:25], v[130:133], v[228:231], v[22:25]
	v_mfma_f32_16x16x32_bf16 v[14:17], v[138:141], v[228:231], v[14:17]
	v_mfma_f32_16x16x32_bf16 v[62:65], v[134:137], v[196:199], v[62:65]
	v_mfma_f32_16x16x32_bf16 v[58:61], v[142:145], v[196:199], v[58:61]
	v_mfma_f32_16x16x32_bf16 v[54:57], v[134:137], v[204:207], v[54:57]
	v_mfma_f32_16x16x32_bf16 v[46:49], v[142:145], v[204:207], v[46:49]
	v_mfma_f32_16x16x32_bf16 v[38:41], v[134:137], v[224:227], v[38:41]
	v_mfma_f32_16x16x32_bf16 v[30:33], v[142:145], v[224:227], v[30:33]
	v_mfma_f32_16x16x32_bf16 v[22:25], v[134:137], v[232:235], v[22:25]
	v_mfma_f32_16x16x32_bf16 v[14:17], v[142:145], v[232:235], v[14:17]
	v_mfma_f32_16x16x32_bf16 v[50:53], v[146:149], v[192:195], v[50:53]
	v_mfma_f32_16x16x32_bf16 v[42:45], v[178:181], v[192:195], v[42:45]
	v_mfma_f32_16x16x32_bf16 v[34:37], v[146:149], v[200:203], v[34:37]
	v_mfma_f32_16x16x32_bf16 v[26:29], v[178:181], v[200:203], v[26:29]
	v_mfma_f32_16x16x32_bf16 v[18:21], v[146:149], v[220:223], v[18:21]
	v_mfma_f32_16x16x32_bf16 v[10:13], v[178:181], v[220:223], v[10:13]
	v_mfma_f32_16x16x32_bf16 v[6:9], v[146:149], v[228:231], v[6:9]
	v_mfma_f32_16x16x32_bf16 v[2:5], v[178:181], v[228:231], v[2:5]
	v_mfma_f32_16x16x32_bf16 v[50:53], v[150:153], v[196:199], v[50:53]
	v_mfma_f32_16x16x32_bf16 v[42:45], v[182:185], v[196:199], v[42:45]
	v_mfma_f32_16x16x32_bf16 v[34:37], v[150:153], v[204:207], v[34:37]
	v_mfma_f32_16x16x32_bf16 v[26:29], v[182:185], v[204:207], v[26:29]
	v_mfma_f32_16x16x32_bf16 v[18:21], v[150:153], v[224:227], v[18:21]
	v_mfma_f32_16x16x32_bf16 v[10:13], v[182:185], v[224:227], v[10:13]
	v_mfma_f32_16x16x32_bf16 v[6:9], v[150:153], v[232:235], v[6:9]
	v_mfma_f32_16x16x32_bf16 v[2:5], v[182:185], v[232:235], v[2:5]
	s_barrier
	s_setprio 0
	s_add_u32 s16, s16, 0x100
	s_addc_u32 s17, s17, 0
	s_cmp_ge_i32 s30, s14
	s_mov_b64 s[48:49], s[26:27]
	s_mov_b32 s28, s30
	s_cbranch_scc1 .Lpeel_exit_4

; #define PG8_BAR __builtin_amdgcn_s_barrier()
; template <class Epi, class Sched, bool ALIGN_EPI = false, bool SP2 = false>
; __device__ __forceinline__ void gemm_phase(PG8_LAS unsigned char* lds, const Gemm g, const Sched& S, const Epi& E) {
;     ...
;         if constexpr (ALIGN_EPI) { if (wr == 0) PG8_BAR; }
;         if constexpr (!Epi::AFTER_DRAIN) { E(acc, cur, wr, wc, fr, fq); S.done(cur); }
.Lpeel_exit_4:
	s_and_b64 vcc, exec, s[40:41]
	s_cbranch_vccz .LBB0_918
	s_barrier
